# scan: staging waves reordered (no mid-chunk vmcnt drains), hand-scheduled recurrence loop with 2-step LDS prefetch and shorter dependent chain; batched pointer-table loads
# speedup vs baseline: 1.0280x; 1.0280x over previous
.LBB0_7:
	s_or_b64 exec, exec, s[6:7]
	v_mov_b32_e32 v4, v254
	v_mov_b64_e32 v[2:3], s[58:59]
	s_barrier
	flat_load_dwordx2 v[6:7], v[2:3] offset:8 sc0 sc1
	flat_load_dwordx2 v[8:9], v[2:3] offset:24 sc0 sc1
	flat_load_dwordx2 v[10:11], v[2:3] offset:32 sc0 sc1
	flat_load_dwordx2 v[12:13], v[2:3] offset:40 sc0 sc1
	s_waitcnt vmcnt(0)
	s_movk_i32 s3, 0x800
	v_cmp_gt_i32_e32 vcc, s3, v4
	s_waitcnt lgkmcnt(0)
	v_readfirstlane_b32 s1, v7
	v_readfirstlane_b32 s0, v6
	v_readfirstlane_b32 s7, v9
	v_readfirstlane_b32 s6, v8
	v_readfirstlane_b32 s15, v11
	v_readfirstlane_b32 s14, v10
	v_readfirstlane_b32 s17, v13
	v_readfirstlane_b32 s16, v12
	s_and_saveexec_b64 s[4:5], vcc
	s_cbranch_execz .LBB0_10
	v_ashrrev_i32_e32 v5, 31, v4
	v_lshlrev_b64 v[6:7], 2, v[4:5]
	v_add_u32_e32 v1, 0xfffffe00, v4
	v_lshl_add_u64 v[2:3], s[6:7], 0, v[6:7]
	v_lshl_add_u64 v[6:7], s[0:1], 0, v[6:7]
	v_lshl_add_u32 v5, v4, 2, 0
	s_mov_b64 s[6:7], 0
	s_mov_b32 s0, 0xbfb8aa3b
	s_mov_b32 s1, 0x42ce8ed0
	s_mov_b32 s3, 0xc2b17218
	v_mov_b32_e32 v8, 0x7f800000
	s_mov_b64 s[8:9], 0x800
	s_movk_i32 s10, 0x5ff

.LBB0_25:
	v_mov_b32_e32 v1, v254
	v_mov_b64_e32 v[2:3], s[58:59]
	flat_load_dwordx2 v[4:5], v[2:3] sc0 sc1
	flat_load_dwordx2 v[6:7], v[2:3] offset:16 sc0 sc1
	s_waitcnt vmcnt(0)
	v_readfirstlane_b32 s0, v1
	s_lshl_b32 s1, s2, 3
	s_ashr_i32 s0, s0, 6
	s_lshl_b32 s22, s30, 3
	v_writelane_b32 v255, s1, 6
	s_add_i32 s1, s0, s1
	s_cmpk_lt_i32 s1, 0x2100
	s_waitcnt lgkmcnt(0)
	v_readfirstlane_b32 s3, v5
	v_readfirstlane_b32 s4, v4
	v_readfirstlane_b32 s5, v7
	v_readfirstlane_b32 s16, v6
	s_cbranch_scc0 .LBB0_30
	v_and_b32_e32 v9, 63, v1
	v_mbcnt_lo_u32_b32 v1, -1, 0
	v_mbcnt_hi_u32_b32 v8, -1, v1
	v_and_b32_e32 v1, 64, v8
	v_readlane_b32 s9, v255, 6
	v_add_u32_e32 v10, 64, v1
	v_xor_b32_e32 v1, 1, v8
	s_ashr_i32 s1, s0, 31
	s_ashr_i32 s8, s9, 31
	v_cmp_lt_i32_e32 vcc, v1, v10
	v_xor_b32_e32 v4, 2, v8
	s_add_u32 s10, s0, s9
	v_cndmask_b32_e32 v1, v8, v1, vcc
	v_cmp_lt_i32_e32 vcc, v4, v10
	v_xor_b32_e32 v5, 4, v8
	s_addc_u32 s11, s1, s8
	v_cndmask_b32_e32 v4, v8, v4, vcc
	v_cmp_lt_i32_e32 vcc, v5, v10
	v_xor_b32_e32 v6, 8, v8
	s_lshl_b64 s[0:1], s[10:11], 2
	v_cndmask_b32_e32 v5, v8, v5, vcc
	v_cmp_lt_i32_e32 vcc, v6, v10
	v_xor_b32_e32 v7, 16, v8
	s_add_u32 s0, s26, s0
	v_cndmask_b32_e32 v6, v8, v6, vcc
	v_cmp_lt_i32_e32 vcc, v7, v10
	v_xor_b32_e32 v11, 32, v8
	s_addc_u32 s1, s27, s1
	v_cndmask_b32_e32 v7, v8, v7, vcc
	v_cmp_lt_i32_e32 vcc, v11, v10
	s_add_u32 s12, s0, 0x40000
	v_lshlrev_b32_e32 v2, 2, v9
	v_cndmask_b32_e32 v8, v8, v11, vcc
	s_addc_u32 s13, s1, 0
	s_ashr_i32 s23, s22, 31
	v_mov_b32_e32 v3, 0
	v_lshlrev_b32_e32 v1, 2, v1
	v_lshlrev_b32_e32 v4, 2, v4
	v_lshlrev_b32_e32 v5, 2, v5
	v_lshlrev_b32_e32 v6, 2, v6
	v_lshlrev_b32_e32 v7, 2, v7
	v_lshlrev_b32_e32 v8, 2, v8
	v_cmp_eq_u32_e64 s[6:7], 0, v9
	s_lshl_b64 s[14:15], s[22:23], 2
	v_lshlrev_b32_e32 v2, 2, v2
	s_movk_i32 s17, 0x1000
	v_mov_b32_e32 v9, 0x358637bd
	s_mov_b32 s18, 0xf800000
	v_mov_b32_e32 v10, 0x260
	s_branch .LBB0_28

.LBB0_100:
	flat_load_dwordx2 v[0:1], v[68:69] offset:48 sc0 sc1
	flat_load_dwordx2 v[2:3], v[68:69] offset:88 sc0 sc1
	flat_load_dwordx2 v[4:5], v[68:69] sc0 sc1
	flat_load_dwordx2 v[6:7], v[68:69] offset:16 sc0 sc1
	s_waitcnt vmcnt(0)
	s_and_b64 vcc, exec, s[6:7]
	s_waitcnt lgkmcnt(0)
	v_readfirstlane_b32 s5, v1
	v_readfirstlane_b32 s4, v0
	v_readfirstlane_b32 s1, v3
	v_readfirstlane_b32 s0, v2
	v_readfirstlane_b32 s63, v5
	v_readfirstlane_b32 s62, v4
	v_readfirstlane_b32 s65, v7
	v_readfirstlane_b32 s64, v6
	s_cbranch_vccnz .LBB0_99
	v_add_u32_e32 v44, s8, v87
	v_ashrrev_i32_e32 v45, 31, v44
	v_lshlrev_b64 v[70:71], 2, v[44:45]
	v_lshl_add_u64 v[36:37], s[0:1], 0, v[70:71]
	s_movk_i32 s0, 0x2000
	v_add_co_u32_e32 v24, vcc, s0, v36
	s_movk_i32 s0, 0x4000
	s_nop 0
	v_addc_co_u32_e32 v25, vcc, 0, v37, vcc
	v_add_co_u32_e32 v28, vcc, s0, v36
	s_movk_i32 s0, 0x6000
	s_nop 0
	v_addc_co_u32_e32 v29, vcc, 0, v37, vcc
	v_add_co_u32_e32 v32, vcc, s0, v36
	s_mov_b32 s0, 0x8000
	s_nop 0
	v_addc_co_u32_e32 v33, vcc, 0, v37, vcc
	v_add_co_u32_e32 v38, vcc, s0, v36
	s_mov_b32 s0, 0xa000
	s_nop 0
	v_addc_co_u32_e32 v39, vcc, 0, v37, vcc
	v_add_co_u32_e32 v40, vcc, s0, v36
	v_lshl_add_u64 v[0:1], s[4:5], 0, v[70:71]
	v_lshl_add_u64 v[4:5], s[40:41], 0, v[70:71]
	v_lshl_add_u64 v[8:9], s[26:27], 0, v[70:71]
	v_lshl_add_u64 v[12:13], s[44:45], 0, v[70:71]
	v_lshl_add_u64 v[16:17], s[42:43], 0, v[70:71]
	v_addc_co_u32_e32 v41, vcc, 0, v37, vcc
	flat_load_dwordx4 v[0:3], v[0:1]
	s_nop 0
	global_load_dwordx4 v[4:7], v[4:5], off
	s_nop 0
	global_load_dwordx4 v[8:11], v[8:9], off
	s_nop 0
	global_load_dwordx4 v[12:15], v[12:13], off
	s_nop 0
	global_load_dwordx4 v[16:19], v[16:17], off
	s_nop 0
	flat_load_dwordx4 v[20:23], v[36:37]
	s_nop 0
	flat_load_dwordx4 v[24:27], v[24:25]
	s_nop 0
	flat_load_dwordx4 v[28:31], v[28:29]
	s_nop 0
	flat_load_dwordx4 v[32:35], v[32:33]
	s_nop 0
	flat_load_dwordx4 v[36:39], v[38:39]
	s_nop 0
	flat_load_dwordx4 v[40:43], v[40:41]
	v_ashrrev_i32_e32 v91, 9, v44
	s_movk_i32 s0, 0x1ff
	v_cmp_gt_i32_e64 s[8:9], 2, v91
	v_cmp_lt_u32_e64 s[10:11], s0, v44
	v_lshlrev_b64 v[44:45], 1, v[44:45]
	v_cndmask_b32_e64 v95, 1, -1, s[8:9]
	v_lshl_add_u64 v[72:73], s[38:39], 0, v[44:45]
	v_lshl_add_u64 v[74:75], s[48:49], 0, v[44:45]
	v_lshl_add_u64 v[76:77], s[50:51], 0, v[44:45]
	v_lshl_add_u64 v[78:79], s[52:53], 0, v[44:45]
	v_lshl_add_u64 v[80:81], s[54:55], 0, v[44:45]
	v_lshl_add_u64 v[82:83], s[56:57], 0, v[44:45]
	s_mov_b32 s66, s2
	s_branch .LBB0_103

.LBB0_178:
	s_or_b64 exec, exec, s[0:1]
	v_mov_b64_e32 v[0:1], s[58:59]
	flat_load_dwordx2 v[4:5], v[0:1] offset:144 sc0 sc1
	flat_load_dwordx2 v[6:7], v[0:1] offset:168 sc0 sc1
	flat_load_dwordx2 v[8:9], v[0:1] offset:184 sc0 sc1
	s_waitcnt vmcnt(0)
	s_mov_b64 s[8:9], 0x280000
	v_cmp_gt_u64_e32 vcc, s[8:9], v[2:3]
	s_waitcnt lgkmcnt(0)
	v_readfirstlane_b32 s24, v5
	v_readfirstlane_b32 s25, v4
	v_readfirstlane_b32 s28, v7
	v_readfirstlane_b32 s29, v6
	v_readfirstlane_b32 s11, v9
	v_readfirstlane_b32 s10, v8
	s_and_saveexec_b64 s[12:13], vcc
	s_cbranch_execz .LBB0_211
	s_mov_b64 s[14:15], 0
	s_mov_b32 s33, 0xcccccccd
	v_mov_b32_e32 v1, 0
	s_movk_i32 s44, 0x1fff
	s_movk_i32 s45, 0xffa0
	s_movk_i32 s46, 0x60
	s_movk_i32 s47, 0x1000
	s_movk_i32 s48, 0x7fff
	s_mov_b64 s[16:17], 0x27ffff
	s_branch .LBB0_185

.LBB0_442:
	s_add_u32 s4, s26, 0x100000
	s_addc_u32 s5, s27, 0
	v_writelane_b32 v255, s4, 16
	s_nop 1
	v_writelane_b32 v255, s5, 17
	s_add_u32 s4, s26, 0x500000
	s_addc_u32 s5, s27, 0
	v_writelane_b32 v255, s4, 18
	s_andn2_b64 vcc, exec, s[0:1]
	s_nop 0
	v_writelane_b32 v255, s5, 19
	s_cbranch_vccnz .LBB0_474
	v_mov_b64_e32 v[0:1], s[58:59]
	flat_load_dwordx2 v[2:3], v[0:1] offset:264 sc0 sc1
	flat_load_dwordx2 v[4:5], v[0:1] offset:272 sc0 sc1
	flat_load_dwordx2 v[6:7], v[0:1] offset:280 sc0 sc1
	flat_load_dwordx2 v[8:9], v[0:1] offset:288 sc0 sc1
	flat_load_dwordx2 v[10:11], v[0:1] offset:296 sc0 sc1
	flat_load_dwordx2 v[12:13], v[0:1] offset:304 sc0 sc1
	flat_load_dwordx2 v[14:15], v[0:1] offset:312 sc0 sc1
	s_waitcnt vmcnt(0)
	s_movk_i32 s0, 0x840
	v_ashrrev_i32_e32 v129, 31, v128
	v_cmp_gt_i32_e32 vcc, s0, v128
	s_waitcnt lgkmcnt(0)
	v_readfirstlane_b32 s43, v3
	v_readfirstlane_b32 s42, v2
	v_readfirstlane_b32 s5, v5
	v_readfirstlane_b32 s4, v4
	v_readfirstlane_b32 s7, v7
	v_readfirstlane_b32 s6, v6
	v_readfirstlane_b32 s13, v9
	v_readfirstlane_b32 s12, v8
	v_readfirstlane_b32 s9, v11
	v_readfirstlane_b32 s8, v10
	v_readfirstlane_b32 s37, v13
	v_readfirstlane_b32 s36, v12
	v_readfirstlane_b32 s1, v15
	v_readfirstlane_b32 s0, v14
	v_lshl_add_u32 v2, v128, 2, 0
	s_and_saveexec_b64 s[10:11], vcc
	s_cbranch_execz .LBB0_446
	v_add_u32_e32 v3, 0x2000, v2
	v_add_u32_e32 v4, 0xfffffe00, v128
	v_lshl_add_u64 v[0:1], v[128:129], 2, s[42:43]
	s_mov_b64 s[42:43], 0
	s_mov_b64 s[44:45], 0x800
	s_movk_i32 s15, 0x63f

.LBB0_527:
	s_or_b64 exec, exec, s[6:7]
	s_waitcnt lgkmcnt(0)
	v_mov_b32_e32 v0, v254
	s_barrier
	s_add_u32 s60, s26, 0x1c900000
	v_mov_b64_e32 v[0:1], s[58:59]
	flat_load_dwordx2 v[2:3], v[0:1] offset:128 sc0 sc1
	flat_load_dwordx2 v[4:5], v[0:1] offset:152 sc0 sc1
	s_waitcnt vmcnt(0)
	s_addc_u32 s61, s27, 0
	s_add_u32 s52, s26, 0x24d00000
	s_addc_u32 s53, s27, 0
	s_add_u32 s56, s26, 0x28f00000
	v_mov_b32_e32 v8, v254
	s_addc_u32 s57, s27, 0
	s_cmpk_lt_i32 s2, 0x528
	v_readfirstlane_b32 s4, v8
	s_waitcnt lgkmcnt(0)
	v_readfirstlane_b32 s41, v3
	v_readfirstlane_b32 s40, v2
	v_readfirstlane_b32 s43, v5
	v_readfirstlane_b32 s42, v4
	s_cbranch_scc0 .LBB0_547
	v_lshlrev_b32_e32 v0, 4, v8
	v_add_u32_e32 v1, 0x2000, v0
	v_ashrrev_i32_e32 v2, 31, v1
	v_lshrrev_b32_e32 v2, 22, v2
	v_add_u32_e32 v2, v1, v2
	v_ashrrev_i32_e32 v2, 10, v2
	v_mul_i32_i24_e32 v3, 0x400, v2
	v_sub_u32_e32 v1, v1, v3
	v_lshrrev_b32_e32 v3, 4, v1
	v_bitop3_b32 v1, v3, v1, 32 bitop3:0x6c
	v_ashrrev_i32_e32 v3, 31, v1
	v_lshrrev_b32_e32 v3, 26, v3
	v_add_u32_e32 v3, v1, v3
	v_lshlrev_b32_e32 v5, 3, v2
	v_ashrrev_i32_e32 v4, 6, v3
	v_and_b32_e32 v5, -16, v5
	v_and_b32_e32 v3, 0xc0, v3
	v_add_u32_e32 v5, v4, v5
	v_sub_u32_e32 v1, v1, v3
	v_mov_b32_e32 v3, 1
	v_and_b32_e32 v4, 3, v4
	s_mov_b32 s6, 0x7fffe0
	v_lshrrev_b32_e32 v6, 2, v5
	v_lshlrev_b32_e32 v7, 1, v5
	v_lshlrev_b32_e32 v2, 5, v2
	v_ashrrev_i16_sdwa v1, v3, sext(v1) dst_sel:DWORD dst_unused:UNUSED_PAD src0_sel:DWORD src1_sel:BYTE_0
	v_and_or_b32 v4, v5, s6, v4
	v_and_b32_e32 v6, 4, v6
	v_and_b32_e32 v7, 24, v7
	v_and_b32_e32 v2, 32, v2
	v_bfe_i32 v1, v1, 0, 16
	v_or3_b32 v4, v4, v6, v7
	v_add_lshl_u32 v1, v2, v1, 1
	v_lshl_add_u32 v136, v4, 9, v1
	v_lshl_add_u32 v138, v5, 9, v1
	v_bfe_i32 v1, v8, 27, 1
	v_lshrrev_b32_e32 v1, 22, v1
	v_add_u32_e32 v1, v0, v1
	v_and_b32_e32 v1, 0xfffffc00, v1
	v_sub_u32_e32 v0, v0, v1
	v_ashrrev_i32_e32 v2, 31, v8
	v_lshrrev_b32_e32 v1, 4, v0
	v_lshrrev_b32_e32 v2, 26, v2
	v_bitop3_b32 v1, v1, v0, 32 bitop3:0x6c
	v_ashrrev_i32_e32 v0, 31, v0
	v_add_u32_e32 v2, v8, v2
	v_lshrrev_b32_e32 v0, 26, v0
	v_ashrrev_i32_e32 v2, 6, v2
	v_add_u32_e32 v0, v1, v0
	v_lshlrev_b32_e32 v4, 3, v2
	v_ashrrev_i32_e32 v0, 6, v0
	v_and_b32_e32 v4, -16, v4
	v_add_u32_e32 v4, v0, v4
	v_and_b32_e32 v5, 3, v0
	v_and_or_b32 v5, v4, s6, v5
	s_lshr_b32 s6, s3, 29
	s_add_i32 s6, s2, s6
	s_ashr_i32 s1, s4, 6
	s_ashr_i32 s7, s6, 3
	s_and_b32 s6, s6, -8
	s_ashr_i32 s0, s4, 8
	s_lshl_b32 s5, s1, 10
	s_sub_i32 s6, s2, s6
	s_cmp_lt_i32 s6, 0
	s_movk_i32 s28, 0xa6
	s_cselect_b32 s8, s28, 0xa5
	s_mul_i32 s6, s6, s8
	s_add_i32 s6, s6, s7
	s_mul_hi_i32 s7, s6, 0x66666667
	s_lshr_b32 s8, s7, 31
	s_ashr_i32 s7, s7, 7
	v_mul_i32_i24_e32 v0, 64, v0
	s_add_i32 s7, s7, s8
	v_sub_u32_e32 v0, v1, v0
	s_lshl_b32 s8, s7, 3
	v_lshlrev_b32_e32 v2, 5, v2
	v_ashrrev_i16_sdwa v0, v3, sext(v0) dst_sel:DWORD dst_unused:UNUSED_PAD src0_sel:DWORD src1_sel:BYTE_0
	s_sub_i32 s9, 33, s8
	s_mulk_i32 s7, 0x140
	v_and_b32_e32 v2, 32, v2
	v_bfe_i32 v0, v0, 0, 16
	s_min_u32 s9, s9, 8
	s_sub_i32 s10, s6, s7
	v_add_lshl_u32 v0, v2, v0, 1
	s_sext_i32_i16 s6, s10
	v_cvt_f32_ubyte0_e32 v2, s9
	v_cvt_f32_i32_e32 v1, s6
	v_rcp_iflag_f32_e32 v3, v2
	v_lshrrev_b32_e32 v6, 2, v4
	v_lshlrev_b32_e32 v7, 1, v4
	v_and_b32_e32 v6, 4, v6
	v_and_b32_e32 v7, 24, v7
	v_or3_b32 v5, v5, v6, v7
	v_lshl_add_u32 v140, v5, 9, v0
	v_lshl_add_u32 v142, v4, 9, v0
	v_mul_f32_e32 v0, v1, v3
	v_trunc_f32_e32 v0, v0
	v_fma_f32 v1, -v0, v2, v1
	v_cvt_i32_f32_e32 v0, v0
	s_ashr_i32 s6, s6, 30
	s_or_b32 s11, s6, 1
	v_cmp_ge_f32_e64 s[6:7], |v1|, v2
	s_and_b64 s[6:7], s[6:7], exec
	s_cselect_b32 s6, s11, 0
	v_readfirstlane_b32 s7, v0
	s_add_i32 s6, s7, s6
	s_mul_i32 s7, s6, s9
	s_sub_i32 s7, s10, s7
	s_sext_i32_i16 s7, s7
	s_add_i32 s10, s8, s7
	s_and_b32 s7, s6, 0xffff
	s_cmp_lt_u32 s7, 32
	s_mov_b32 s29, 0x420000
	s_sext_i32_i16 s20, s6
	s_cselect_b32 s7, s29, 0x840000
	s_cmp_gt_i32 s20, 15
	s_cselect_b32 s12, s7, 0
	s_ashr_i32 s11, s10, 31
	s_bfe_i64 s[6:7], s[6:7], 0x100000
	s_lshl_b64 s[8:9], s[10:11], 17
	s_lshl_b64 s[6:7], s[6:7], 17
	s_add_u32 s14, s18, s6
	s_addc_u32 s15, s19, s7
	s_add_i32 s36, s5, 0
	s_add_i32 m0, s36, 0x10000
	v_mov_b32_e32 v145, 0
	global_load_lds_dwordx4 v140, s[14:15]
	s_add_i32 m0, s36, 0x12000
	s_add_u32 s6, s16, s12
	s_addc_u32 s7, s17, 0
	s_add_u32 s12, s6, s8
	global_load_lds_dwordx4 v136, s[14:15]
	s_addc_u32 s13, s7, s9
	s_mov_b32 m0, s36
	s_add_i32 s37, s36, 0x2000
	global_load_lds_dwordx4 v142, s[12:13]
	s_mov_b32 m0, s37
	s_add_u32 s6, s14, 0x10000
	global_load_lds_dwordx4 v138, s[12:13]
	s_addc_u32 s7, s15, 0
	s_add_i32 m0, s36, 0x14000
	v_mov_b32_e32 v141, v145
	global_load_lds_dwordx4 v140, s[6:7]
	s_add_i32 m0, s36, 0x16000
	v_mov_b32_e32 v137, v145
	global_load_lds_dwordx4 v136, s[6:7]
	s_add_u32 s6, s12, 0x10000
	s_addc_u32 s7, s13, 0
	s_add_i32 s50, s36, 0x4000
	s_mov_b32 m0, s50
	s_add_i32 s51, s36, 0x6000
	global_load_lds_dwordx4 v142, s[6:7]
	s_mov_b32 m0, s51
	v_mov_b32_e32 v143, v145
	global_load_lds_dwordx4 v138, s[6:7]
	v_mov_b32_e32 v139, v145
	v_lshl_add_u64 v[6:7], s[14:15], 0, v[140:141]
	v_lshl_add_u64 v[4:5], s[14:15], 0, v[136:137]
	v_lshl_add_u64 v[2:3], s[12:13], 0, v[142:143]
	s_cmp_lg_u32 s0, 1
	v_lshl_add_u64 v[0:1], s[12:13], 0, v[138:139]
	s_cbranch_scc1 .LBB0_530
	s_barrier

.LBB0_600:
	v_writelane_b32 v255, s88, 20
	s_nop 1
	v_writelane_b32 v255, s89, 21
	s_or_b64 exec, exec, s[6:7]
	s_waitcnt lgkmcnt(0)
	v_mov_b32_e32 v0, v254
	v_mov_b64_e32 v[2:3], s[58:59]
	s_barrier
	flat_load_dwordx2 v[4:5], v[2:3] offset:192 sc0 sc1
	flat_load_dwordx2 v[6:7], v[2:3] offset:200 sc0 sc1
	s_waitcnt vmcnt(0)
	s_add_u32 s66, s26, 0x13800000
	s_addc_u32 s67, s27, 0
	s_add_u32 s68, s26, 0x15900000
	s_addc_u32 s69, s27, 0
	s_add_u32 s64, s26, 0x2800000
	s_addc_u32 s65, s27, 0
	s_add_u32 s4, s26, 0x2dc00000
	s_addc_u32 s5, s27, 0
	v_writelane_b32 v255, s4, 22
	v_readfirstlane_b32 s0, v0
	s_waitcnt lgkmcnt(0)
	v_readfirstlane_b32 s71, v5
	v_writelane_b32 v255, s5, 23
	s_add_u32 s4, s26, 0x2b000000
	s_addc_u32 s5, s27, 0
	v_writelane_b32 v255, s4, 24
	v_readfirstlane_b32 s70, v4
	v_readfirstlane_b32 s73, v7
	v_writelane_b32 v255, s5, 25
	s_add_u32 s4, s26, 0x12a00000
	s_addc_u32 s5, s27, 0
	s_add_u32 s54, s26, 0x11200000
	v_writelane_b32 v255, s4, 26
	s_addc_u32 s55, s27, 0
	s_add_u32 s58, s26, 0x5c00000
	v_writelane_b32 v255, s5, 27
	s_addc_u32 s59, s27, 0
	v_readlane_b32 s4, v255, 7
	s_add_u32 s62, s26, 0x3000000
	v_readlane_b32 s5, v255, 8
	s_addc_u32 s63, s27, 0
	s_and_b64 vcc, exec, s[4:5]
	v_readfirstlane_b32 s72, v6
	s_cbranch_vccz .LBB0_732
	v_readlane_b32 s4, v255, 10
	v_readlane_b32 s5, v255, 11
	s_nop 1
	v_mov_b64_e32 v[2:3], s[4:5]
	flat_load_dwordx2 v[4:5], v[2:3] offset:80 sc0 sc1
	flat_load_dwordx2 v[6:7], v[2:3] offset:72 sc0 sc1
	flat_load_dwordx2 v[8:9], v[2:3] offset:64 sc0 sc1
	flat_load_dwordx2 v[10:11], v[2:3] offset:336 sc0 sc1
	flat_load_dwordx2 v[12:13], v[2:3] offset:232 sc0 sc1
	flat_load_dwordx2 v[14:15], v[2:3] offset:120 sc0 sc1
	s_waitcnt vmcnt(0) lgkmcnt(0)
	v_readfirstlane_b32 s76, v4
	v_readfirstlane_b32 s77, v5
	v_readfirstlane_b32 s78, v6
	v_readfirstlane_b32 s79, v7
	v_readfirstlane_b32 s80, v8
	v_readfirstlane_b32 s81, v9
	v_readfirstlane_b32 s82, v10
	v_readfirstlane_b32 s83, v11
	v_readfirstlane_b32 s84, v12
	v_readfirstlane_b32 s85, v13
	v_readfirstlane_b32 s6, v14
	v_readfirstlane_b32 s7, v15
	s_ashr_i32 s0, s0, 6
	v_and_b32_e32 v2, 15, v0
	v_bfe_u32 v131, v0, 4, 4
	s_add_i32 s23, s0, -4
	s_mulk_i32 s0, 0x2100
	v_lshlrev_b32_e32 v6, 3, v0
	v_lshlrev_b32_e32 v4, 8, v131
	v_lshlrev_b32_e32 v5, 4, v2
	s_add_i32 s0, s0, 0
	v_bfe_u32 v148, v0, 3, 3
	v_and_b32_e32 v6, 56, v6
	v_writelane_b32 v255, s6, 28
	s_movk_i32 s1, 0xff
	v_or_b32_e32 v136, 16, v131
	v_add3_u32 v141, 0, v4, v5
	v_and_b32_e32 v4, 0xf0, v0
	s_add_i32 s0, s0, 0x14c00
	v_mul_u32_u24_e32 v10, 0x84, v6
	v_lshlrev_b32_e32 v11, 2, v148
	v_writelane_b32 v255, s7, 29
	v_cmp_lt_i32_e64 s[6:7], s1, v0
	s_movk_i32 s1, 0x100
	v_lshlrev_b32_e32 v142, 2, v4
	v_lshlrev_b32_e32 v4, 8, v136
	v_add3_u32 v149, s0, v10, v11
	v_mov_b32_e32 v10, 5
	v_ashrrev_i32_e32 v99, 4, v0
	v_cmp_gt_i32_e64 s[8:9], s1, v0
	v_add3_u32 v145, 0, v4, v5
	v_and_b32_e32 v7, 7, v0
	v_bfe_u32 v147, v0, 5, 1
	v_and_b32_e32 v4, 31, v0
	v_lshlrev_b32_sdwa v153, v10, v0 dst_sel:DWORD dst_unused:UNUSED_PAD src0_sel:DWORD src1_sel:BYTE_0
	v_or_b32_sdwa v0, v0, s1 dst_sel:DWORD dst_unused:UNUSED_PAD src0_sel:BYTE_0 src1_sel:DWORD
	s_movk_i32 s4, 0x20ff
	v_lshrrev_b32_e32 v154, 4, v0
	v_lshlrev_b32_e32 v155, 5, v0
	v_mov_b32_e32 v0, 0xa040
	v_bitop3_b32 v140, v131, s4, 16 bitop3:0x36
	v_lshlrev_b32_e32 v3, 6, v131
	s_movk_i32 s4, 0xff40
	v_lshl_add_u32 v8, v4, 2, s0
	v_mul_u32_u24_e32 v9, 0x84, v147
	v_lshl_add_u32 v160, v99, 2, v0
	v_lshlrev_b32_e32 v0, 2, v7
	v_lshlrev_b32_e32 v98, 2, v2
	v_or_b32_e32 v137, 0x2000, v131
	v_xor_b32_e32 v138, 0x20ff, v131
	v_cmp_gt_u32_e64 s[10:11], 4, v2
	v_mov_b32_e32 v1, 0
	v_or_b32_e32 v139, 0x2010, v131
	s_mov_b32 s87, 0
	v_add3_u32 v143, 0, v142, v5
	v_lshlrev_b32_e32 v144, 6, v136
	v_mad_i32_i24 v146, v136, s4, v145
	v_or_b32_e32 v150, 8, v148
	v_or_b32_e32 v151, 16, v148
	v_or_b32_e32 v152, 24, v148
	v_or_b32_e32 v156, 0x1fe0, v131
	v_xor_b32_e32 v157, 31, v131
	v_or_b32_e32 v158, 0x1fe0, v154
	v_xor_b32_e32 v159, 31, v154
	v_or_b32_e32 v161, 0x100, v5
	v_lshl_or_b32 v162, v99, 5, v0
	s_mov_b32 s74, 0xf800000
	v_mov_b32_e32 v163, 0x260
	v_lshlrev_b32_e32 v100, 1, v2
	s_mov_b32 s75, 0xa800
	s_movk_i32 s40, 0x7fff
	s_mov_b32 s41, 0xac00
	s_movk_i32 s20, 0x15ff
	s_movk_i32 s21, 0x2bff
	s_movk_i32 s46, 0x41ff
	s_movk_i32 s47, 0x59ff
	s_movk_i32 s24, 0x61ff
	s_movk_i32 s44, 0x77ff
	s_mov_b32 s45, 0x8dff
	v_add_u32_e32 v164, v8, v9
	v_lshlrev_b32_e32 v102, 1, v6
	v_lshlrev_b32_e32 v104, 2, v4
	v_lshlrev_b32_e32 v165, 2, v3
	s_add_i32 s25, 0, 0x19000
	v_mov_b32_e32 v166, 7
	v_mov_b32_e32 v167, 0xa800
	s_mov_b32 s33, s2
	s_branch .LBB0_603

.LBB0_615:
	s_or_b64 exec, exec, s[16:17]
	s_and_b64 s[0:1], s[12:13], exec
	s_mov_b32 s0, 0x7200000
	s_cselect_b32 s0, s0, 0xb200000
	s_add_u32 s0, s26, s0
	s_addc_u32 s1, s27, 0
	s_lshl_b32 s5, s28, 1
	s_add_u32 s0, s0, s5
	s_addc_u32 s1, s1, 0
	s_lshl_b32 s4, s4, 5
	s_add_u32 s0, s0, s4
	s_addc_u32 s1, s1, 0
	v_mov_b32_e32 v101, v1
	v_lshl_add_u64 v[118:119], s[0:1], 0, v[100:101]
	s_add_u32 s0, s68, s5
	s_addc_u32 s1, s69, 0
	v_lshl_add_u64 v[6:7], v[4:5], 2, s[60:61]
	v_lshl_add_u64 v[4:5], v[4:5], 1, s[52:53]
	v_mov_b32_e32 v3, v1
	s_add_u32 s0, s0, s4
	v_lshl_add_u64 v[120:121], s[48:49], 0, v[0:1]
	v_lshl_add_u64 v[122:123], v[6:7], 0, v[0:1]
	v_lshl_add_u64 v[124:125], v[4:5], 0, v[2:3]
	v_lshl_add_u64 v[126:127], s[66:67], 0, v[2:3]
	s_addc_u32 s1, s1, 0
	v_lshlrev_b32_e32 v0, 1, v98
	v_mov_b32_e32 v2, v1
	v_mov_b32_e32 v4, v1
	v_mov_b32_e32 v5, v1
	v_mov_b32_e32 v6, v1
	v_mov_b32_e32 v7, v1
	v_mov_b32_e32 v8, v1
	v_mov_b32_e32 v9, v1
	v_mov_b32_e32 v10, v1
	v_mov_b32_e32 v11, v1
	v_mov_b32_e32 v12, v1
	v_mov_b32_e32 v13, v1
	v_mov_b32_e32 v14, v1
	v_mov_b32_e32 v15, v1
	v_mov_b32_e32 v16, v1
	v_mov_b32_e32 v17, v1
	v_mov_b32_e32 v18, v1
	v_mov_b32_e32 v19, v1
	v_mov_b32_e32 v20, v1
	v_mov_b32_e32 v21, v1
	v_mov_b32_e32 v22, v1
	v_mov_b32_e32 v23, v1
	v_mov_b32_e32 v24, v1
	v_mov_b32_e32 v25, v1
	v_mov_b32_e32 v26, v1
	v_mov_b32_e32 v27, v1
	v_mov_b32_e32 v28, v1
	v_mov_b32_e32 v29, v1
	v_mov_b32_e32 v30, v1
	v_mov_b32_e32 v31, v1
	v_lshl_add_u64 v[128:129], s[0:1], 0, v[0:1]
	v_mov_b32_e32 v0, v1
	v_mov_b32_e32 v78, v1
	v_mov_b32_e32 v79, v1
	v_mov_b64_e32 v[32:33], v[30:31]
	v_mov_b32_e32 v101, 0
	s_mov_b64 s[90:91], 0
	v_mov_b64_e32 v[80:81], v[78:79]
	v_mov_b64_e32 v[30:31], v[28:29]
	v_mov_b64_e32 v[28:29], v[26:27]
	v_mov_b64_e32 v[26:27], v[24:25]
	v_mov_b64_e32 v[24:25], v[22:23]
	v_mov_b64_e32 v[22:23], v[20:21]
	v_mov_b64_e32 v[20:21], v[18:19]
	v_mov_b64_e32 v[18:19], v[16:17]
	v_mov_b64_e32 v[16:17], v[14:15]
	v_mov_b64_e32 v[14:15], v[12:13]
	v_mov_b64_e32 v[12:13], v[10:11]
	v_mov_b64_e32 v[10:11], v[8:9]
	v_mov_b64_e32 v[8:9], v[6:7]
	v_mov_b64_e32 v[6:7], v[4:5]
	v_mov_b64_e32 v[4:5], v[2:3]
	v_mov_b64_e32 v[2:3], v[0:1]
	s_and_saveexec_b64 s[36:37], s[6:7]
	s_cbranch_execz .Lscan_pro_load_done
	v_mov_b32_e32 v64, 1
	v_lshlrev_b32_e32 v0, 5, v64
	v_or_b32_e32 v34, v0, v131
	v_cmp_lt_u32_e64 s[18:19], 5, v101
	s_and_saveexec_b64 s[0:1], s[18:19]
	s_xor_b64 s[0:1], exec, s[0:1]
	s_cbranch_execz .Lscan_pro_634
	s_mov_b64 s[4:5], -1
	s_and_b64 vcc, exec, s[88:89]
	s_cbranch_vccz .Lscan_pro_631
	v_sub_u32_e32 v50, 0x20ff, v34
	s_mov_b64 s[4:5], 0

.Lscan_pro_load_done:
	s_or_b64 exec, exec, s[36:37]
	s_waitcnt lgkmcnt(0)
	s_barrier
	s_branch .LBB0_619

.LBB0_619:
	s_and_saveexec_b64 s[0:1], s[8:9]
	s_xor_b64 s[14:15], exec, s[0:1]
	s_cbranch_execz .LBB0_623
	v_and_b32_e32 v87, 1, v101
	v_mad_u32_u24 v0, v87, s75, 0
	v_lshl_add_u32 v84, v98, 2, v0
	v_lshl_add_u32 v85, v99, 2, v0
	v_lshl_add_u32 v86, v87, 14, v162
	ds_read_b128 v[2:5], v84 offset:0
	ds_read_b128 v[6:9], v84 offset:8192
	ds_read_b128 v[10:13], v84 offset:16384
	ds_read_b128 v[14:17], v84 offset:24576
	ds_read_b128 v[18:21], v84 offset:32768
	ds_read_b32 v22, v85 offset:40960
	ds_read_b128 v[24:27], v84 offset:256
	ds_read_b128 v[28:31], v84 offset:8448
	ds_read_b128 v[32:35], v84 offset:16640
	ds_read_b128 v[36:39], v84 offset:24832
	ds_read_b128 v[40:43], v84 offset:33024
	ds_read_b32 v44, v85 offset:41024
	v_add_u32_e32 v86, 0x15000, v86
	s_mov_b32 s0, 4
	s_waitcnt lgkmcnt(6)
.Lscan_rec_loop:
	v_pk_mul_f32 v[68:69], v[2:3], v[78:79]
	v_pk_mul_f32 v[70:71], v[22:23], v[14:15] op_sel_hi:[0,1]
	v_pk_mul_f32 v[72:73], v[22:23], v[16:17] op_sel_hi:[0,1]
	v_pk_fma_f32 v[68:69], v[4:5], v[80:81], v[68:69]
	v_pk_fma_f32 v[74:75], v[6:7], v[78:79], v[70:71]
	v_pk_fma_f32 v[76:77], v[8:9], v[80:81], v[72:73]
	v_add_f32_e32 v68, v68, v69
	ds_read_b128 v[46:49], v84 offset:512
	ds_read_b128 v[50:53], v84 offset:8704
	v_add_f32_dpp v68, v68, v68 quad_perm:[1,0,3,2] row_mask:0xf bank_mask:0xf bound_ctrl:1
	ds_read_b128 v[54:57], v84 offset:16896
	ds_read_b128 v[58:61], v84 offset:25088
	v_add_f32_dpp v68, v68, v68 quad_perm:[2,3,0,1] row_mask:0xf bank_mask:0xf bound_ctrl:1
	ds_read_b128 v[62:65], v84 offset:33280
	ds_read_b32 v66, v85 offset:41088
	v_add_f32_dpp v68, v68, v68 row_half_mirror row_mask:0xf bank_mask:0xf bound_ctrl:1
	s_nop 1
	v_add_f32_dpp v68, v68, v68 row_ror:8 row_mask:0xf bank_mask:0xf bound_ctrl:1
	v_pk_fma_f32 v[78:79], v[10:11], v[68:69], v[74:75] op_sel_hi:[1,0,1] neg_lo:[0,1,0] neg_hi:[0,1,0]
	v_pk_fma_f32 v[80:81], v[12:13], v[68:69], v[76:77] op_sel_hi:[1,0,1] neg_lo:[0,1,0] neg_hi:[0,1,0]
	s_waitcnt lgkmcnt(6)
	v_pk_mul_f32 v[68:69], v[24:25], v[78:79]
	v_pk_mul_f32 v[82:83], v[18:19], v[78:79]
	v_pk_mul_f32 v[70:71], v[44:45], v[36:37] op_sel_hi:[0,1]
	v_pk_fma_f32 v[68:69], v[26:27], v[80:81], v[68:69]
	v_pk_fma_f32 v[82:83], v[20:21], v[80:81], v[82:83]
	v_pk_mul_f32 v[72:73], v[44:45], v[38:39] op_sel_hi:[0,1]
	v_add_f32_e32 v68, v68, v69
	v_add_f32_e32 v82, v82, v83
	v_pk_fma_f32 v[74:75], v[28:29], v[78:79], v[70:71]
	v_add_f32_dpp v68, v68, v68 quad_perm:[1,0,3,2] row_mask:0xf bank_mask:0xf bound_ctrl:1
	v_add_f32_dpp v82, v82, v82 row_ror:8 row_mask:0xf bank_mask:0xf bound_ctrl:1
	v_pk_fma_f32 v[76:77], v[30:31], v[80:81], v[72:73]
	v_add_f32_dpp v68, v68, v68 quad_perm:[2,3,0,1] row_mask:0xf bank_mask:0xf bound_ctrl:1
	ds_write_b32 v86, v82 offset:0
	ds_read_b128 v[106:109], v84 offset:768
	v_add_f32_dpp v68, v68, v68 row_half_mirror row_mask:0xf bank_mask:0xf bound_ctrl:1
	ds_read_b128 v[110:113], v84 offset:8960
	ds_read_b128 v[114:117], v84 offset:17152
	v_add_f32_dpp v68, v68, v68 row_ror:8 row_mask:0xf bank_mask:0xf bound_ctrl:1
	ds_read_b128 v[118:121], v84 offset:25344
	ds_read_b128 v[122:125], v84 offset:33536
	ds_read_b32 v126, v85 offset:41152
	v_pk_fma_f32 v[78:79], v[32:33], v[68:69], v[74:75] op_sel_hi:[1,0,1] neg_lo:[0,1,0] neg_hi:[0,1,0]
	v_pk_fma_f32 v[80:81], v[34:35], v[68:69], v[76:77] op_sel_hi:[1,0,1] neg_lo:[0,1,0] neg_hi:[0,1,0]
	s_waitcnt lgkmcnt(6)
	v_pk_mul_f32 v[68:69], v[46:47], v[78:79]
	v_pk_mul_f32 v[82:83], v[40:41], v[78:79]
	v_pk_mul_f32 v[70:71], v[66:67], v[58:59] op_sel_hi:[0,1]
	v_pk_fma_f32 v[68:69], v[48:49], v[80:81], v[68:69]
	v_pk_fma_f32 v[82:83], v[42:43], v[80:81], v[82:83]
	v_pk_mul_f32 v[72:73], v[66:67], v[60:61] op_sel_hi:[0,1]
	v_add_f32_e32 v68, v68, v69
	v_add_f32_e32 v82, v82, v83
	v_pk_fma_f32 v[74:75], v[50:51], v[78:79], v[70:71]
	v_add_f32_dpp v68, v68, v68 quad_perm:[1,0,3,2] row_mask:0xf bank_mask:0xf bound_ctrl:1
	v_add_f32_dpp v82, v82, v82 row_ror:8 row_mask:0xf bank_mask:0xf bound_ctrl:1
	v_pk_fma_f32 v[76:77], v[52:53], v[80:81], v[72:73]
	v_add_f32_dpp v68, v68, v68 quad_perm:[2,3,0,1] row_mask:0xf bank_mask:0xf bound_ctrl:1
	ds_write_b32 v86, v82 offset:512
	ds_read_b128 v[2:5], v84 offset:1024
	v_add_f32_dpp v68, v68, v68 row_half_mirror row_mask:0xf bank_mask:0xf bound_ctrl:1
	ds_read_b128 v[6:9], v84 offset:9216
	ds_read_b128 v[10:13], v84 offset:17408
	v_add_f32_dpp v68, v68, v68 row_ror:8 row_mask:0xf bank_mask:0xf bound_ctrl:1
	ds_read_b128 v[14:17], v84 offset:25600
	ds_read_b128 v[18:21], v84 offset:33792
	ds_read_b32 v22, v85 offset:41216
	v_pk_fma_f32 v[78:79], v[54:55], v[68:69], v[74:75] op_sel_hi:[1,0,1] neg_lo:[0,1,0] neg_hi:[0,1,0]
	v_pk_fma_f32 v[80:81], v[56:57], v[68:69], v[76:77] op_sel_hi:[1,0,1] neg_lo:[0,1,0] neg_hi:[0,1,0]
	s_waitcnt lgkmcnt(6)
	v_pk_mul_f32 v[68:69], v[106:107], v[78:79]
	v_pk_mul_f32 v[82:83], v[62:63], v[78:79]
	v_pk_mul_f32 v[70:71], v[126:127], v[118:119] op_sel_hi:[0,1]
	v_pk_fma_f32 v[68:69], v[108:109], v[80:81], v[68:69]
	v_pk_fma_f32 v[82:83], v[64:65], v[80:81], v[82:83]
	v_pk_mul_f32 v[72:73], v[126:127], v[120:121] op_sel_hi:[0,1]
	v_add_f32_e32 v68, v68, v69
	v_add_f32_e32 v82, v82, v83
	v_pk_fma_f32 v[74:75], v[110:111], v[78:79], v[70:71]
	v_add_f32_dpp v68, v68, v68 quad_perm:[1,0,3,2] row_mask:0xf bank_mask:0xf bound_ctrl:1
	v_add_f32_dpp v82, v82, v82 row_ror:8 row_mask:0xf bank_mask:0xf bound_ctrl:1
	v_pk_fma_f32 v[76:77], v[112:113], v[80:81], v[72:73]
	v_add_f32_dpp v68, v68, v68 quad_perm:[2,3,0,1] row_mask:0xf bank_mask:0xf bound_ctrl:1
	ds_write_b32 v86, v82 offset:1024
	ds_read_b128 v[24:27], v84 offset:1280
	v_add_f32_dpp v68, v68, v68 row_half_mirror row_mask:0xf bank_mask:0xf bound_ctrl:1
	ds_read_b128 v[28:31], v84 offset:9472
	ds_read_b128 v[32:35], v84 offset:17664
	v_add_f32_dpp v68, v68, v68 row_ror:8 row_mask:0xf bank_mask:0xf bound_ctrl:1
	ds_read_b128 v[36:39], v84 offset:25856
	ds_read_b128 v[40:43], v84 offset:34048
	ds_read_b32 v44, v85 offset:41280
	v_pk_fma_f32 v[78:79], v[114:115], v[68:69], v[74:75] op_sel_hi:[1,0,1] neg_lo:[0,1,0] neg_hi:[0,1,0]
	v_pk_fma_f32 v[80:81], v[116:117], v[68:69], v[76:77] op_sel_hi:[1,0,1] neg_lo:[0,1,0] neg_hi:[0,1,0]
	s_waitcnt lgkmcnt(6)
	v_pk_mul_f32 v[68:69], v[2:3], v[78:79]
	v_pk_mul_f32 v[82:83], v[122:123], v[78:79]
	v_pk_mul_f32 v[70:71], v[22:23], v[14:15] op_sel_hi:[0,1]
	v_pk_fma_f32 v[68:69], v[4:5], v[80:81], v[68:69]
	v_pk_fma_f32 v[82:83], v[124:125], v[80:81], v[82:83]
	v_pk_mul_f32 v[72:73], v[22:23], v[16:17] op_sel_hi:[0,1]
	v_add_f32_e32 v68, v68, v69
	v_add_f32_e32 v82, v82, v83
	v_pk_fma_f32 v[74:75], v[6:7], v[78:79], v[70:71]
	v_add_f32_dpp v68, v68, v68 quad_perm:[1,0,3,2] row_mask:0xf bank_mask:0xf bound_ctrl:1
	v_add_f32_dpp v82, v82, v82 row_ror:8 row_mask:0xf bank_mask:0xf bound_ctrl:1
	v_pk_fma_f32 v[76:77], v[8:9], v[80:81], v[72:73]
	v_add_f32_dpp v68, v68, v68 quad_perm:[2,3,0,1] row_mask:0xf bank_mask:0xf bound_ctrl:1
	ds_write_b32 v86, v82 offset:1536
	ds_read_b128 v[46:49], v84 offset:1536
	v_add_f32_dpp v68, v68, v68 row_half_mirror row_mask:0xf bank_mask:0xf bound_ctrl:1
	ds_read_b128 v[50:53], v84 offset:9728
	ds_read_b128 v[54:57], v84 offset:17920
	v_add_f32_dpp v68, v68, v68 row_ror:8 row_mask:0xf bank_mask:0xf bound_ctrl:1
	ds_read_b128 v[58:61], v84 offset:26112
	ds_read_b128 v[62:65], v84 offset:34304
	ds_read_b32 v66, v85 offset:41344
	v_pk_fma_f32 v[78:79], v[10:11], v[68:69], v[74:75] op_sel_hi:[1,0,1] neg_lo:[0,1,0] neg_hi:[0,1,0]
	v_pk_fma_f32 v[80:81], v[12:13], v[68:69], v[76:77] op_sel_hi:[1,0,1] neg_lo:[0,1,0] neg_hi:[0,1,0]
	s_waitcnt lgkmcnt(6)
	v_pk_mul_f32 v[68:69], v[24:25], v[78:79]
	v_pk_mul_f32 v[82:83], v[18:19], v[78:79]
	v_pk_mul_f32 v[70:71], v[44:45], v[36:37] op_sel_hi:[0,1]
	v_pk_fma_f32 v[68:69], v[26:27], v[80:81], v[68:69]
	v_pk_fma_f32 v[82:83], v[20:21], v[80:81], v[82:83]
	v_pk_mul_f32 v[72:73], v[44:45], v[38:39] op_sel_hi:[0,1]
	v_add_f32_e32 v68, v68, v69
	v_add_f32_e32 v82, v82, v83
	v_pk_fma_f32 v[74:75], v[28:29], v[78:79], v[70:71]
	v_add_f32_dpp v68, v68, v68 quad_perm:[1,0,3,2] row_mask:0xf bank_mask:0xf bound_ctrl:1
	v_add_f32_dpp v82, v82, v82 row_ror:8 row_mask:0xf bank_mask:0xf bound_ctrl:1
	v_pk_fma_f32 v[76:77], v[30:31], v[80:81], v[72:73]
	v_add_f32_dpp v68, v68, v68 quad_perm:[2,3,0,1] row_mask:0xf bank_mask:0xf bound_ctrl:1
	ds_write_b32 v86, v82 offset:2048
	ds_read_b128 v[106:109], v84 offset:1792
	v_add_f32_dpp v68, v68, v68 row_half_mirror row_mask:0xf bank_mask:0xf bound_ctrl:1
	ds_read_b128 v[110:113], v84 offset:9984
	ds_read_b128 v[114:117], v84 offset:18176
	v_add_f32_dpp v68, v68, v68 row_ror:8 row_mask:0xf bank_mask:0xf bound_ctrl:1
	ds_read_b128 v[118:121], v84 offset:26368
	ds_read_b128 v[122:125], v84 offset:34560
	ds_read_b32 v126, v85 offset:41408
	v_pk_fma_f32 v[78:79], v[32:33], v[68:69], v[74:75] op_sel_hi:[1,0,1] neg_lo:[0,1,0] neg_hi:[0,1,0]
	v_pk_fma_f32 v[80:81], v[34:35], v[68:69], v[76:77] op_sel_hi:[1,0,1] neg_lo:[0,1,0] neg_hi:[0,1,0]
	s_waitcnt lgkmcnt(6)
	v_pk_mul_f32 v[68:69], v[46:47], v[78:79]
	v_pk_mul_f32 v[82:83], v[40:41], v[78:79]
	v_pk_mul_f32 v[70:71], v[66:67], v[58:59] op_sel_hi:[0,1]
	v_pk_fma_f32 v[68:69], v[48:49], v[80:81], v[68:69]
	v_pk_fma_f32 v[82:83], v[42:43], v[80:81], v[82:83]
	v_pk_mul_f32 v[72:73], v[66:67], v[60:61] op_sel_hi:[0,1]
	v_add_f32_e32 v68, v68, v69
	v_add_f32_e32 v82, v82, v83
	v_pk_fma_f32 v[74:75], v[50:51], v[78:79], v[70:71]
	v_add_f32_dpp v68, v68, v68 quad_perm:[1,0,3,2] row_mask:0xf bank_mask:0xf bound_ctrl:1
	v_add_f32_dpp v82, v82, v82 row_ror:8 row_mask:0xf bank_mask:0xf bound_ctrl:1
	v_pk_fma_f32 v[76:77], v[52:53], v[80:81], v[72:73]
	v_add_f32_dpp v68, v68, v68 quad_perm:[2,3,0,1] row_mask:0xf bank_mask:0xf bound_ctrl:1
	ds_write_b32 v86, v82 offset:2560
	ds_read_b128 v[2:5], v84 offset:2048
	v_add_f32_dpp v68, v68, v68 row_half_mirror row_mask:0xf bank_mask:0xf bound_ctrl:1
	ds_read_b128 v[6:9], v84 offset:10240
	ds_read_b128 v[10:13], v84 offset:18432
	v_add_f32_dpp v68, v68, v68 row_ror:8 row_mask:0xf bank_mask:0xf bound_ctrl:1
	ds_read_b128 v[14:17], v84 offset:26624
	ds_read_b128 v[18:21], v84 offset:34816
	ds_read_b32 v22, v85 offset:41472
	v_pk_fma_f32 v[78:79], v[54:55], v[68:69], v[74:75] op_sel_hi:[1,0,1] neg_lo:[0,1,0] neg_hi:[0,1,0]
	v_pk_fma_f32 v[80:81], v[56:57], v[68:69], v[76:77] op_sel_hi:[1,0,1] neg_lo:[0,1,0] neg_hi:[0,1,0]
	s_waitcnt lgkmcnt(6)
	v_pk_mul_f32 v[68:69], v[106:107], v[78:79]
	v_pk_mul_f32 v[82:83], v[62:63], v[78:79]
	v_pk_mul_f32 v[70:71], v[126:127], v[118:119] op_sel_hi:[0,1]
	v_pk_fma_f32 v[68:69], v[108:109], v[80:81], v[68:69]
	v_pk_fma_f32 v[82:83], v[64:65], v[80:81], v[82:83]
	v_pk_mul_f32 v[72:73], v[126:127], v[120:121] op_sel_hi:[0,1]
	v_add_f32_e32 v68, v68, v69
	v_add_f32_e32 v82, v82, v83
	v_pk_fma_f32 v[74:75], v[110:111], v[78:79], v[70:71]
	v_add_f32_dpp v68, v68, v68 quad_perm:[1,0,3,2] row_mask:0xf bank_mask:0xf bound_ctrl:1
	v_add_f32_dpp v82, v82, v82 row_ror:8 row_mask:0xf bank_mask:0xf bound_ctrl:1
	v_pk_fma_f32 v[76:77], v[112:113], v[80:81], v[72:73]
	v_add_f32_dpp v68, v68, v68 quad_perm:[2,3,0,1] row_mask:0xf bank_mask:0xf bound_ctrl:1
	ds_write_b32 v86, v82 offset:3072
	ds_read_b128 v[24:27], v84 offset:2304
	v_add_f32_dpp v68, v68, v68 row_half_mirror row_mask:0xf bank_mask:0xf bound_ctrl:1
	ds_read_b128 v[28:31], v84 offset:10496
	ds_read_b128 v[32:35], v84 offset:18688
	v_add_f32_dpp v68, v68, v68 row_ror:8 row_mask:0xf bank_mask:0xf bound_ctrl:1
	ds_read_b128 v[36:39], v84 offset:26880
	ds_read_b128 v[40:43], v84 offset:35072
	ds_read_b32 v44, v85 offset:41536
	v_pk_fma_f32 v[78:79], v[114:115], v[68:69], v[74:75] op_sel_hi:[1,0,1] neg_lo:[0,1,0] neg_hi:[0,1,0]
	v_pk_fma_f32 v[80:81], v[116:117], v[68:69], v[76:77] op_sel_hi:[1,0,1] neg_lo:[0,1,0] neg_hi:[0,1,0]
	s_waitcnt lgkmcnt(6)
	v_pk_mul_f32 v[82:83], v[122:123], v[78:79]
	v_pk_fma_f32 v[82:83], v[124:125], v[80:81], v[82:83]
	s_sub_u32 s0, s0, 1
	v_add_u32_e32 v84, 0x800, v84
	v_add_f32_e32 v82, v82, v83
	v_add_u32_e32 v85, 0x200, v85
	s_cmp_lg_u32 s0, 0
	v_add_f32_dpp v82, v82, v82 row_ror:8 row_mask:0xf bank_mask:0xf bound_ctrl:1
	ds_write_b32 v86, v82 offset:3584
	v_add_u32_e32 v86, 0x1000, v86
	s_cbranch_scc1 .Lscan_rec_loop
	v_add_u32_e32 v101, 1, v101
.LBB0_623:
	s_andn2_saveexec_b64 s[92:93], s[14:15]
	s_cbranch_execz .LBB0_618
	s_waitcnt vmcnt(0) lgkmcnt(0)
	s_movk_i32 s0, 0x107
	v_add_u32_e32 v64, 1, v101
	v_cmp_ne_u32_e64 s[14:15], s0, v101
	s_and_saveexec_b64 s[16:17], s[14:15]
	s_cbranch_execz .Lscan_stage_done
	v_pk_mul_f32 v[60:61], v[42:43], v[34:35]
	v_pk_mul_f32 v[58:59], v[44:45], v[36:37]
	v_pk_mul_f32 v[66:67], v[60:61], v[60:61]
	v_pk_mul_f32 v[62:63], v[58:59], v[58:59]
	v_add_f32_e32 v0, v66, v67
	v_add_f32_e32 v0, v62, v0
	v_add_f32_e32 v0, v63, v0
	v_and_b32_e32 v63, 1, v64
	v_lshlrev_b32_e32 v70, 16, v111
	v_add_f32_dpp v0, v0, v0 quad_perm:[1,0,3,2] row_mask:0xf bank_mask:0xf bound_ctrl:1
	v_and_b32_e32 v71, 0xffff0000, v111
	v_lshlrev_b32_e32 v74, 16, v112
	v_add_f32_dpp v0, v0, v0 quad_perm:[2,3,0,1] row_mask:0xf bank_mask:0xf bound_ctrl:1
	v_and_b32_e32 v75, 0xffff0000, v112
	v_lshlrev_b32_e32 v76, 16, v113
	v_add_f32_dpp v0, v0, v0 row_half_mirror row_mask:0xf bank_mask:0xf bound_ctrl:1
	v_and_b32_e32 v77, 0xffff0000, v113
	s_nop 0
	v_add_f32_dpp v0, v0, v0 row_ror:8 row_mask:0xf bank_mask:0xf bound_ctrl:1
	v_mul_f32_e32 v62, 0x4f800000, v0
	v_cmp_gt_f32_e32 vcc, s74, v0
	s_nop 1
	v_cndmask_b32_e32 v0, v0, v62, vcc
	v_sqrt_f32_e32 v62, v0
	s_nop 0
	v_add_u32_e32 v65, -1, v62
	v_fma_f32 v66, -v65, v62, v0
	v_cmp_ge_f32_e64 s[14:15], 0, v66
	v_add_u32_e32 v66, 1, v62
	s_nop 0
	v_cndmask_b32_e64 v65, v62, v65, s[14:15]
	v_fma_f32 v62, -v66, v62, v0
	v_cmp_lt_f32_e64 s[14:15], 0, v62
	s_nop 1
	v_cndmask_b32_e64 v62, v65, v66, s[14:15]
	v_mul_f32_e32 v65, 0x37800000, v62
	v_cndmask_b32_e32 v62, v62, v65, vcc
	v_cmp_class_f32_e32 vcc, v0, v163
	s_nop 1
	v_cndmask_b32_e32 v0, v62, v0, vcc
	v_max_f32_e32 v62, 0x2b8cbccc, v0
	v_div_scale_f32 v65, s[0:1], v62, v62, 1.0
	v_rcp_f32_e32 v66, v65
	v_cmp_eq_u32_e32 vcc, 1, v63
	v_fma_f32 v63, -v65, v66, 1.0
	s_nop 0
	v_cndmask_b32_e32 v0, 0, v167, vcc
	v_fmac_f32_e32 v66, v63, v66
	v_div_scale_f32 v63, vcc, 1.0, v62, 1.0
	v_mul_f32_e32 v67, v63, v66
	v_fma_f32 v68, -v65, v67, v63
	v_fmac_f32_e32 v67, v68, v66
	v_fma_f32 v63, -v65, v67, v63
	v_div_fmas_f32 v63, v63, v66, v67
	v_div_fixup_f32 v66, v63, v62, 1.0
	v_pk_mul_f32 v[62:63], v[58:59], v[66:67] op_sel_hi:[1,0]
	v_lshlrev_b32_e32 v58, 16, v110
	v_and_b32_e32 v59, 0xffff0000, v110
	v_pk_mul_f32 v[60:61], v[60:61], v[66:67] op_sel_hi:[1,0]
	v_pk_add_f32 v[66:67], v[70:71], -1.0 op_sel_hi:[1,0]
	v_pk_add_f32 v[68:69], v[58:59], -1.0 op_sel_hi:[1,0]
	v_pk_fma_f32 v[66:67], v[48:49], v[66:67], 1.0 op_sel_hi:[1,1,0]
	v_pk_fma_f32 v[72:73], v[46:47], v[68:69], 1.0 op_sel_hi:[1,1,0]
	v_add_u32_e32 v0, 0, v0
	v_pk_mul_f32 v[68:69], v[36:37], v[66:67]
	v_pk_mul_f32 v[66:67], v[34:35], v[72:73]
	v_pk_mul_f32 v[72:73], v[62:63], v[70:71]
	v_pk_mul_f32 v[70:71], v[60:61], v[58:59]
	v_lshlrev_b32_e32 v58, 2, v98
	v_add3_u32 v59, v0, v165, v58
	ds_write_b128 v59, v[60:63]
	ds_write_b128 v59, v[38:41] offset:8192
	ds_write_b128 v59, v[70:73] offset:16384
	ds_write_b128 v59, v[66:69] offset:24576
	ds_write_b128 v59, v[74:77] offset:32768
	s_and_saveexec_b64 s[0:1], s[10:11]
	s_cbranch_execz .LBB0_728
	v_lshlrev_b32_e32 v60, 16, v106
	v_and_b32_e32 v61, 0xffff0000, v106
	v_lshlrev_b32_e32 v62, 16, v107
	v_and_b32_e32 v63, 0xffff0000, v107
	v_add3_u32 v59, v0, v142, v58
	ds_write_b128 v59, v[60:63] offset:40960
.LBB0_728:
	s_or_b64 exec, exec, s[0:1]
	v_pk_mul_f32 v[66:67], v[42:43], v[50:51]
	v_pk_mul_f32 v[60:61], v[44:45], v[52:53]
	v_pk_mul_f32 v[68:69], v[66:67], v[66:67]
	v_pk_mul_f32 v[62:63], v[60:61], v[60:61]
	v_add_f32_e32 v59, v68, v69
	v_add_f32_e32 v59, v62, v59
	v_add_f32_e32 v59, v63, v59
	v_lshlrev_b32_e32 v70, 16, v114
	v_and_b32_e32 v71, 0xffff0000, v114
	v_add_f32_dpp v59, v59, v59 quad_perm:[1,0,3,2] row_mask:0xf bank_mask:0xf bound_ctrl:1
	v_lshlrev_b32_e32 v72, 16, v115
	v_and_b32_e32 v73, 0xffff0000, v115
	v_add_f32_dpp v59, v59, v59 quad_perm:[2,3,0,1] row_mask:0xf bank_mask:0xf bound_ctrl:1
	v_lshlrev_b32_e32 v76, 16, v117
	v_and_b32_e32 v77, 0xffff0000, v117
	v_add_f32_dpp v59, v59, v59 row_half_mirror row_mask:0xf bank_mask:0xf bound_ctrl:1
	s_nop 1
	v_add_f32_dpp v59, v59, v59 row_ror:8 row_mask:0xf bank_mask:0xf bound_ctrl:1
	v_mul_f32_e32 v62, 0x4f800000, v59
	v_cmp_gt_f32_e32 vcc, s74, v59
	s_nop 1
	v_cndmask_b32_e32 v59, v59, v62, vcc
	v_sqrt_f32_e32 v62, v59
	s_nop 0
	v_add_u32_e32 v63, -1, v62
	v_fma_f32 v65, -v63, v62, v59
	v_cmp_ge_f32_e64 s[14:15], 0, v65
	v_add_u32_e32 v65, 1, v62
	s_nop 0
	v_cndmask_b32_e64 v63, v62, v63, s[14:15]
	v_fma_f32 v62, -v65, v62, v59
	v_cmp_lt_f32_e64 s[14:15], 0, v62
	s_nop 1
	v_cndmask_b32_e64 v62, v63, v65, s[14:15]
	v_mul_f32_e32 v63, 0x37800000, v62
	v_cndmask_b32_e32 v62, v62, v63, vcc
	v_cmp_class_f32_e32 vcc, v59, v163
	s_nop 1
	v_cndmask_b32_e32 v59, v62, v59, vcc
	v_max_f32_e32 v59, 0x2b8cbccc, v59
	v_div_scale_f32 v62, s[0:1], v59, v59, 1.0
	v_rcp_f32_e32 v63, v62
	s_nop 0
	v_fma_f32 v65, -v62, v63, 1.0
	v_fmac_f32_e32 v63, v65, v63
	v_div_scale_f32 v65, vcc, 1.0, v59, 1.0
	v_mul_f32_e32 v68, v65, v63
	v_fma_f32 v69, -v62, v68, v65
	v_fmac_f32_e32 v68, v69, v63
	v_fma_f32 v62, -v62, v68, v65
	v_div_fmas_f32 v62, v62, v63, v68
	v_div_fixup_f32 v68, v62, v59, 1.0
	v_pk_mul_f32 v[62:63], v[60:61], v[68:69] op_sel_hi:[1,0]
	v_pk_mul_f32 v[60:61], v[66:67], v[68:69] op_sel_hi:[1,0]
	v_pk_add_f32 v[66:67], v[72:73], -1.0 op_sel_hi:[1,0]
	v_pk_add_f32 v[68:69], v[70:71], -1.0 op_sel_hi:[1,0]
	v_lshlrev_b32_e32 v59, 2, v144
	v_pk_fma_f32 v[74:75], v[46:47], v[68:69], 1.0 op_sel_hi:[1,1,0]
	v_pk_fma_f32 v[66:67], v[48:49], v[66:67], 1.0 op_sel_hi:[1,1,0]
	v_add3_u32 v59, v0, v59, v58
	v_pk_mul_f32 v[68:69], v[52:53], v[66:67]
	v_pk_mul_f32 v[66:67], v[50:51], v[74:75]
	v_pk_mul_f32 v[72:73], v[62:63], v[72:73]
	v_pk_mul_f32 v[70:71], v[60:61], v[70:71]
	v_lshlrev_b32_e32 v74, 16, v116
	v_and_b32_e32 v75, 0xffff0000, v116
	ds_write_b128 v59, v[60:63]
	ds_write_b128 v59, v[54:57] offset:8192
	ds_write_b128 v59, v[70:73] offset:16384
	ds_write_b128 v59, v[66:69] offset:24576
	ds_write_b128 v59, v[74:77] offset:32768
	s_and_saveexec_b64 s[0:1], s[10:11]
	s_cbranch_execz .Lscan_stage_tail
	v_lshlrev_b32_e32 v60, 16, v108
	v_and_b32_e32 v61, 0xffff0000, v108
	v_lshlrev_b32_e32 v62, 16, v109
	v_and_b32_e32 v63, 0xffff0000, v109
	v_add3_u32 v0, v0, v144, v58
	ds_write_b128 v0, v[60:63] offset:40960
.Lscan_stage_tail:
	s_or_b64 exec, exec, s[0:1]
.Lscan_stage_done:
	s_or_b64 exec, exec, s[16:17]
	s_movk_i32 s0, 0x106
	v_add_u32_e32 v64, 2, v101
	v_cmp_gt_u32_e64 s[14:15], s0, v101
	s_and_saveexec_b64 s[36:37], s[14:15]
	s_cbranch_execz .Lscan_load_done
	v_lshlrev_b32_e32 v0, 5, v64
	v_or_b32_e32 v34, v0, v131
	v_cmp_lt_u32_e64 s[18:19], 5, v101
	s_and_saveexec_b64 s[0:1], s[18:19]
	s_xor_b64 s[0:1], exec, s[0:1]
	s_cbranch_execz .LBB0_634
	s_mov_b64 s[4:5], -1
	s_and_b64 vcc, exec, s[88:89]
	s_cbranch_vccz .LBB0_631
	v_sub_u32_e32 v50, 0x20ff, v34
	s_mov_b64 s[4:5], 0

.Lscan_load_done:
	s_or_b64 exec, exec, s[36:37]
	v_cmp_ne_u32_e64 s[16:17], 0, v101
	v_add_u32_e32 v60, -1, v101
	s_and_saveexec_b64 s[0:1], s[16:17]
	s_cbranch_execz .LBB0_627
	v_cmp_lt_u32_e32 vcc, 7, v60
	s_and_b64 exec, exec, vcc
	s_cbranch_execz .LBB0_627
	v_lshlrev_b32_e32 v0, 14, v60
	s_add_i32 s4, 0, 0x15000
	v_and_b32_e32 v0, 0x4000, v0
	v_add_u32_e32 v70, s4, v0
	v_add_u32_e32 v0, v70, v153
	ds_read_b128 v[62:65], v0
	ds_read_b128 v[66:69], v0 offset:16
	v_lshlrev_b32_e32 v61, 5, v60
	v_or_b32_e32 v0, v131, v61
	v_add_u32_e32 v58, 0xffffff00, v0
	v_sub_u32_e32 v0, 0x20ff, v0
	v_cndmask_b32_e64 v0, v0, v58, s[12:13]
	s_waitcnt lgkmcnt(0)
	v_pk_add_f32 v[58:59], v[64:65], v[68:69]
	v_pk_add_f32 v[62:63], v[62:63], v[66:67]
	v_add_f32_e32 v58, v58, v59
	v_add_f32_e32 v62, v62, v63
	v_add_f32_e32 v58, v62, v58
	v_bfe_u32 v59, v58, 16, 1
	v_add3_u32 v62, v58, v59, s40
	v_lshlrev_b64 v[58:59], 12, v[0:1]
	v_lshl_add_u64 v[58:59], v[118:119], 0, v[58:59]
	global_store_short_d16_hi v[58:59], v62, off
	v_add_u32_e32 v0, v70, v155
	ds_read_b128 v[62:65], v0
	ds_read_b128 v[66:69], v0 offset:16
	v_or_b32_e32 v0, v154, v61
	v_add_u32_e32 v58, 0xffffff00, v0
	v_sub_u32_e32 v0, 0x20ff, v0
	v_cndmask_b32_e64 v0, v0, v58, s[12:13]
	s_waitcnt lgkmcnt(0)
	v_pk_add_f32 v[58:59], v[64:65], v[68:69]
	v_pk_add_f32 v[62:63], v[62:63], v[66:67]
	v_add_f32_e32 v58, v58, v59
	v_add_f32_e32 v61, v62, v63
	v_add_f32_e32 v58, v61, v58
	v_bfe_u32 v59, v58, 16, 1
	v_add3_u32 v61, v58, v59, s40
	v_lshlrev_b64 v[58:59], 12, v[0:1]
	v_lshl_add_u64 v[58:59], v[118:119], 0, v[58:59]
	global_store_short_d16_hi v[58:59], v61, off
.LBB0_627:
	s_or_b64 exec, exec, s[0:1]
	v_add_u32_e32 v64, 1, v101
	v_mul_lo_u32 v0, v60, s30
	v_add_u32_e32 v0, s2, v0
	v_lshl_add_u32 v0, v0, 2, s23
	v_cmp_gt_u32_e32 vcc, s41, v0
	s_and_b64 s[0:1], s[16:17], vcc
	s_and_saveexec_b64 s[16:17], s[0:1]
	s_cbranch_execz .LBB0_691
	v_cmp_lt_u32_e32 vcc, s20, v0
	v_mov_b32_e32 v66, 0xb0
	v_mov_b64_e32 v[58:59], 0x800
	s_mov_b64 s[0:1], 0
	v_mov_b32_e32 v65, 0
	v_mov_b64_e32 v[62:63], s[80:81]
	v_mov_b64_e32 v[60:61], s[62:63]
	s_and_saveexec_b64 s[18:19], vcc
	s_cbranch_execz .LBB0_686
	v_cmp_lt_u32_e32 vcc, s21, v0
	v_mov_b64_e32 v[62:63], s[78:79]
	s_and_saveexec_b64 s[0:1], vcc
	s_xor_b64 s[94:95], exec, s[0:1]
	s_cbranch_execz .LBB0_683
	v_cmp_lt_u32_e32 vcc, s46, v0
	v_mov_b64_e32 v[62:63], s[76:77]
	s_and_saveexec_b64 s[0:1], vcc
	s_xor_b64 s[50:51], exec, s[0:1]
	s_cbranch_execz .LBB0_680
	v_cmp_lt_u32_e32 vcc, s47, v0
	v_mov_b64_e32 v[62:63], s[84:85]
	s_and_saveexec_b64 s[0:1], vcc
	s_xor_b64 s[36:37], exec, s[0:1]
	s_cbranch_execz .LBB0_677
	v_cmp_lt_u32_e32 vcc, s24, v0
	v_mov_b64_e32 v[62:63], s[82:83]
	s_and_saveexec_b64 s[0:1], vcc
	s_xor_b64 s[4:5], exec, s[0:1]
	s_cbranch_execz .LBB0_674
	v_cmp_lt_u32_e32 vcc, s44, v0
	v_mov_b64_e32 v[62:63], s[80:81]
	s_and_saveexec_b64 s[0:1], vcc
	s_xor_b64 s[0:1], exec, s[0:1]
	s_cbranch_execz .LBB0_671
	v_cmp_lt_u32_e32 vcc, s45, v0
	v_mov_b64_e32 v[62:63], s[78:79]
	s_and_saveexec_b64 s[28:29], vcc
	s_xor_b64 s[96:97], exec, s[28:29]
	s_cbranch_execz .LBB0_668
	s_mov_b32 s28, 0xa3ff
	v_cmp_lt_u32_e32 vcc, s28, v0
	v_mov_b64_e32 v[62:63], s[76:77]
	s_and_saveexec_b64 s[28:29], vcc
	s_xor_b64 s[28:29], exec, s[28:29]
	s_cbranch_execz .LBB0_665
	v_readlane_b32 s42, v255, 28
	v_readlane_b32 s43, v255, 29
	v_add_u32_e32 v0, 0xffff5c00, v0
	s_nop 0
	v_mov_b64_e32 v[62:63], s[42:43]

.LBB0_686:
	s_or_b64 exec, exec, s[18:19]
	s_waitcnt lgkmcnt(0)
	v_cvt_f32_u32_sdwa v63, v66 dst_sel:DWORD dst_unused:UNUSED_PAD src0_sel:WORD_0
	v_cvt_f32_u32_sdwa v62, v0 dst_sel:DWORD dst_unused:UNUSED_PAD src0_sel:WORD_0
	s_xor_b64 s[0:1], s[0:1], -1
	v_rcp_iflag_f32_e32 v67, v63
	s_nop 0
	v_mul_f32_e32 v67, v62, v67
	v_trunc_f32_e32 v67, v67
	v_fma_f32 v62, -v67, v63, v62
	v_cvt_u32_f32_e32 v67, v67
	v_cmp_ge_f32_e64 vcc, |v62|, v63
	s_nop 1
	v_addc_co_u32_e32 v63, vcc, 0, v67, vcc
	v_mul_lo_u16_e32 v62, v63, v66
	v_sub_u16_e32 v66, v0, v62
	v_lshlrev_b32_e32 v0, 5, v66
	s_and_saveexec_b64 s[4:5], s[0:1]
	s_xor_b64 s[0:1], exec, s[4:5]
	v_lshlrev_b32_e32 v62, 6, v66
	v_and_b32_e32 v62, 0x3f00, v62
	v_and_b32_e32 v0, 0x60, v0
	v_or3_b32 v62, v0, v62, v65
	s_andn2_saveexec_b64 s[0:1], s[0:1]
	v_add_u32_e32 v62, v0, v65
	s_or_b64 exec, exec, s[0:1]
	v_add_u32_e32 v0, 0x400, v164
	ds_write2_b32 v164, v2, v3 offset1:66
	ds_write2_b32 v164, v4, v5 offset0:132 offset1:198
	ds_write2_b32 v0, v6, v7 offset0:8 offset1:74
	ds_write2_b32 v0, v8, v9 offset0:140 offset1:206
	v_add_u32_e32 v0, 0x800, v164
	ds_write2_b32 v0, v10, v11 offset0:16 offset1:82
	ds_write2_b32 v0, v12, v13 offset0:148 offset1:214
	v_add_u32_e32 v0, 0xc00, v164
	ds_write2_b32 v0, v14, v15 offset0:24 offset1:90
	ds_write2_b32 v0, v16, v17 offset0:156 offset1:222
	v_add_u32_e32 v0, 0x1000, v164
	ds_write2_b32 v0, v18, v19 offset0:32 offset1:98
	ds_write2_b32 v0, v20, v21 offset0:164 offset1:230
	v_add_u32_e32 v0, 0x1400, v164
	ds_write2_b32 v0, v22, v23 offset0:40 offset1:106
	ds_write2_b32 v0, v24, v25 offset0:172 offset1:238
	v_add_u32_e32 v0, 0x1800, v164
	ds_write2_b32 v0, v26, v27 offset0:48 offset1:114
	ds_write2_b32 v0, v28, v29 offset0:180 offset1:246
	v_add_u32_e32 v0, 0x1c00, v164
	ds_write2_b32 v0, v30, v31 offset0:56 offset1:122
	ds_write2_b32 v0, v32, v33 offset0:188 offset1:254
	s_waitcnt lgkmcnt(0)
	ds_read2_b32 v[66:67], v149 offset1:33
	s_waitcnt lgkmcnt(0)
	s_nop 1
	v_cvt_pk_bf16_f32 v66, v66, v67
	ds_read2_b32 v[68:69], v149 offset0:66 offset1:99
	s_waitcnt lgkmcnt(0)
	s_nop 1
	v_cvt_pk_bf16_f32 v67, v68, v69
	ds_read2_b32 v[68:69], v149 offset0:132 offset1:165
	v_lshlrev_b32_sdwa v0, v166, v63 dst_sel:DWORD dst_unused:UNUSED_PAD src0_sel:DWORD src1_sel:WORD_0
	s_waitcnt lgkmcnt(0)
	s_nop 1
	v_cvt_pk_bf16_f32 v68, v68, v69
	ds_read2_b32 v[70:71], v149 offset0:198 offset1:231
	v_add_u32_e32 v63, v62, v148
	s_waitcnt lgkmcnt(0)
	s_nop 1
	v_cvt_pk_bf16_f32 v69, v70, v71
	v_mad_u64_u32 v[70:71], s[0:1], v58, v63, 0
	v_lshl_add_u64 v[60:61], v[60:61], 0, v[0:1]
	v_mov_b32_e32 v0, v71
	v_mov_b32_e32 v103, v1
	v_mad_u64_u32 v[72:73], s[0:1], v59, v63, v[0:1]
	v_lshl_add_u64 v[60:61], v[60:61], 0, v[102:103]
	v_mov_b32_e32 v71, v72
	v_lshl_add_u64 v[70:71], v[70:71], 1, v[60:61]
	global_store_dwordx4 v[70:71], v[66:69], off
	ds_read2_b32 v[66:67], v149 offset0:8 offset1:41
	v_add_u32_e32 v63, v62, v150
	s_waitcnt lgkmcnt(0)
	s_nop 1
	v_cvt_pk_bf16_f32 v66, v66, v67
	ds_read2_b32 v[68:69], v149 offset0:74 offset1:107
	s_waitcnt lgkmcnt(0)
	s_nop 1
	v_cvt_pk_bf16_f32 v67, v68, v69
	ds_read2_b32 v[68:69], v149 offset0:140 offset1:173
	s_waitcnt lgkmcnt(0)
	s_nop 1
	v_cvt_pk_bf16_f32 v68, v68, v69
	ds_read2_b32 v[70:71], v149 offset0:206 offset1:239
	s_waitcnt lgkmcnt(0)
	s_nop 1
	v_cvt_pk_bf16_f32 v69, v70, v71
	v_mad_u64_u32 v[70:71], s[0:1], v58, v63, 0
	v_mov_b32_e32 v0, v71
	v_mad_u64_u32 v[72:73], s[0:1], v59, v63, v[0:1]
	v_mov_b32_e32 v71, v72
	v_lshl_add_u64 v[70:71], v[70:71], 1, v[60:61]
	global_store_dwordx4 v[70:71], v[66:69], off
	ds_read2_b32 v[66:67], v149 offset0:16 offset1:49
	v_add_u32_e32 v63, v62, v151
	s_waitcnt lgkmcnt(0)
	s_nop 1
	v_cvt_pk_bf16_f32 v66, v66, v67
	ds_read2_b32 v[68:69], v149 offset0:82 offset1:115
	s_waitcnt lgkmcnt(0)
	s_nop 1
	v_cvt_pk_bf16_f32 v67, v68, v69
	ds_read2_b32 v[68:69], v149 offset0:148 offset1:181
	s_waitcnt lgkmcnt(0)
	s_nop 1
	v_cvt_pk_bf16_f32 v68, v68, v69
	ds_read2_b32 v[70:71], v149 offset0:214 offset1:247
	s_waitcnt lgkmcnt(0)
	s_nop 1
	v_cvt_pk_bf16_f32 v69, v70, v71
	v_mad_u64_u32 v[70:71], s[0:1], v58, v63, 0
	v_mov_b32_e32 v0, v71
	v_mad_u64_u32 v[72:73], s[0:1], v59, v63, v[0:1]
	v_add_u32_e32 v65, v62, v152
	v_mov_b32_e32 v71, v72
	v_mad_u64_u32 v[62:63], s[0:1], v58, v65, 0
	v_lshl_add_u64 v[70:71], v[70:71], 1, v[60:61]
	v_mov_b32_e32 v0, v63
	global_store_dwordx4 v[70:71], v[66:69], off
	ds_read2_b32 v[66:67], v149 offset0:24 offset1:57
	v_mad_u64_u32 v[58:59], s[0:1], v59, v65, v[0:1]
	s_waitcnt lgkmcnt(0)
	s_nop 1
	v_cvt_pk_bf16_f32 v66, v66, v67
	ds_read2_b32 v[68:69], v149 offset0:90 offset1:123
	v_mov_b32_e32 v63, v58
	s_waitcnt lgkmcnt(0)
	s_nop 1
	v_cvt_pk_bf16_f32 v67, v68, v69
	ds_read2_b32 v[68:69], v149 offset0:156 offset1:189
	v_lshl_add_u64 v[58:59], v[62:63], 1, v[60:61]
	s_waitcnt lgkmcnt(0)
	s_nop 1
	v_cvt_pk_bf16_f32 v68, v68, v69
	ds_read2_b32 v[70:71], v149 offset0:222 offset1:255
	s_waitcnt lgkmcnt(0)
	s_nop 1
	v_cvt_pk_bf16_f32 v69, v70, v71
	global_store_dwordx4 v[58:59], v[66:69], off
	s_waitcnt lgkmcnt(0)
.LBB0_691:
	s_or_b64 exec, exec, s[16:17]
	v_mul_lo_u32 v0, v101, s30
	v_add_u32_e32 v0, s2, v0
	v_lshl_add_u32 v0, v0, 2, s23
	v_cmp_gt_u32_e32 vcc, s41, v0
	s_and_saveexec_b64 s[16:17], vcc
	s_cbranch_execz .LBB0_725
	v_readfirstlane_b32 s0, v0
	s_mov_b64 s[4:5], s[80:81]
	s_movk_i32 s28, 0x1600
	s_cmp_lt_u32 s0, 0x1600
	s_cbranch_scc1 .Lscan_ph1_sel
	s_sub_u32 s0, s0, 0x1600
	s_mov_b64 s[4:5], s[78:79]
	s_cmp_lt_u32 s0, 0x1600
	s_cbranch_scc1 .Lscan_ph1_sel
	s_sub_u32 s0, s0, 0x1600
	s_mov_b64 s[4:5], s[76:77]
	s_movk_i32 s28, 0x800
	s_cmp_lt_u32 s0, 0x1600
	s_cbranch_scc1 .Lscan_ph1_sel
	s_sub_u32 s0, s0, 0x1600
	s_mov_b64 s[4:5], s[84:85]
	s_movk_i32 s28, 0x1800
	s_cmp_lt_u32 s0, 0x1800
	s_cbranch_scc1 .Lscan_ph1_sel
	s_sub_u32 s0, s0, 0x1800
	s_mov_b64 s[4:5], s[82:83]
	s_movk_i32 s28, 0x800
	s_cmp_lt_u32 s0, 0x800
	s_cbranch_scc1 .Lscan_ph1_sel
	s_sub_u32 s0, s0, 0x800
	s_add_u32 s4, s80, 0x2c00000
	s_addc_u32 s5, s81, 0
	s_movk_i32 s28, 0x1600
	s_cmp_lt_u32 s0, 0x1600
	s_cbranch_scc1 .Lscan_ph1_sel
	s_sub_u32 s0, s0, 0x1600
	s_add_u32 s4, s78, 0x2c00000
	s_addc_u32 s5, s79, 0
	s_cmp_lt_u32 s0, 0x1600
	s_cbranch_scc1 .Lscan_ph1_sel
	s_sub_u32 s0, s0, 0x1600
	s_add_u32 s4, s76, 0x2c00000
	s_addc_u32 s5, s77, 0
	s_movk_i32 s28, 0x800
	s_cmp_lt_u32 s0, 0x1600
	s_cbranch_scc1 .Lscan_ph1_sel
	s_sub_u32 s0, s0, 0x1600
	v_readlane_b32 s4, v255, 28
	v_readlane_b32 s5, v255, 29
.Lscan_ph1_sel:
	v_mov_b32_e32 v0, s0
	v_mov_b32_e32 v33, s28
	v_mov_b64_e32 v[2:3], s[4:5]
	v_lshrrev_b32_e32 v4, 5, v33
	v_cvt_f32_u32_e32 v6, v4
	v_cvt_f32_u32_sdwa v5, v0 dst_sel:DWORD dst_unused:UNUSED_PAD src0_sel:WORD_0
	v_mov_b32_e32 v105, v1
	v_rcp_iflag_f32_e32 v7, v6
	s_nop 0
	v_mul_f32_e32 v7, v5, v7
	v_trunc_f32_e32 v7, v7
	v_fma_f32 v5, -v7, v6, v5
	v_cvt_u32_f32_e32 v7, v7
	v_cmp_ge_f32_e64 vcc, |v5|, v6
	s_nop 1
	v_addc_co_u32_e32 v5, vcc, 0, v7, vcc
	v_and_b32_e32 v6, 0xffff, v5
	v_mul_lo_u16_e32 v4, v5, v4
	v_sub_u16_e32 v0, v0, v4
	v_lshl_or_b32 v4, v6, 6, v147
	v_mul_hi_u32_u24_e32 v5, v4, v33
	v_mul_u32_u24_e32 v4, v4, v33
	v_lshlrev_b16_e32 v0, 5, v0
	v_lshl_add_u64 v[2:3], v[4:5], 2, v[2:3]
	v_lshlrev_b32_e32 v0, 2, v0
	v_lshl_add_u64 v[2:3], v[2:3], 0, v[0:1]
	v_lshl_add_u64 v[58:59], v[2:3], 0, v[104:105]
	v_lshlrev_b32_e32 v0, 1, v33
	v_lshl_add_u64 v[4:5], v[0:1], 2, v[58:59]
	v_lshlrev_b32_e32 v0, 2, v33
	flat_load_dword v2, v[58:59] nt
	flat_load_dword v3, v[4:5] nt
	v_lshl_add_u64 v[4:5], v[0:1], 2, v[58:59]
	v_mul_u32_u24_e32 v0, 6, v33
	v_lshlrev_b32_e32 v0, 2, v0
	v_lshl_add_u64 v[6:7], v[58:59], 0, v[0:1]
	v_lshlrev_b32_e32 v0, 3, v33
	flat_load_dword v4, v[4:5] nt
	s_nop 0
	flat_load_dword v5, v[6:7] nt
	v_lshl_add_u64 v[6:7], v[0:1], 2, v[58:59]
	v_mul_u32_u24_e32 v0, 10, v33
	v_lshlrev_b32_e32 v0, 2, v0
	v_lshl_add_u64 v[8:9], v[58:59], 0, v[0:1]
	v_mul_u32_u24_e32 v0, 12, v33
	v_lshlrev_b32_e32 v0, 2, v0
	flat_load_dword v6, v[6:7] nt
	s_nop 0
	flat_load_dword v7, v[8:9] nt
	v_lshl_add_u64 v[8:9], v[58:59], 0, v[0:1]
	v_mul_u32_u24_e32 v0, 14, v33
	v_lshlrev_b32_e32 v0, 2, v0
	v_lshl_add_u64 v[10:11], v[58:59], 0, v[0:1]
	v_lshlrev_b32_e32 v0, 4, v33
	flat_load_dword v8, v[8:9] nt
	s_nop 0
	flat_load_dword v9, v[10:11] nt
	v_lshl_add_u64 v[10:11], v[0:1], 2, v[58:59]
	v_mul_u32_u24_e32 v0, 18, v33
	v_lshlrev_b32_e32 v0, 2, v0
	v_lshl_add_u64 v[12:13], v[58:59], 0, v[0:1]
	v_mul_u32_u24_e32 v0, 20, v33
	v_lshlrev_b32_e32 v0, 2, v0
	flat_load_dword v10, v[10:11] nt
	s_nop 0
	flat_load_dword v11, v[12:13] nt
	v_lshl_add_u64 v[12:13], v[58:59], 0, v[0:1]
	v_mul_u32_u24_e32 v0, 22, v33
	v_lshlrev_b32_e32 v0, 2, v0
	v_lshl_add_u64 v[14:15], v[58:59], 0, v[0:1]
	v_mul_u32_u24_e32 v0, 24, v33
	v_lshlrev_b32_e32 v0, 2, v0
	flat_load_dword v12, v[12:13] nt
	s_nop 0
	flat_load_dword v13, v[14:15] nt
	v_lshl_add_u64 v[14:15], v[58:59], 0, v[0:1]
	v_mul_u32_u24_e32 v0, 26, v33
	v_lshlrev_b32_e32 v0, 2, v0
	v_lshl_add_u64 v[16:17], v[58:59], 0, v[0:1]
	v_mul_u32_u24_e32 v0, 28, v33
	v_lshlrev_b32_e32 v0, 2, v0
	flat_load_dword v14, v[14:15] nt
	s_nop 0
	flat_load_dword v15, v[16:17] nt
	v_lshl_add_u64 v[16:17], v[58:59], 0, v[0:1]
	v_mul_u32_u24_e32 v0, 30, v33
	v_lshlrev_b32_e32 v0, 2, v0
	v_lshl_add_u64 v[18:19], v[58:59], 0, v[0:1]
	v_lshlrev_b32_e32 v0, 5, v33
	flat_load_dword v16, v[16:17] nt
	s_nop 0
	flat_load_dword v17, v[18:19] nt
	v_lshl_add_u64 v[18:19], v[0:1], 2, v[58:59]
	v_mul_u32_u24_e32 v0, 34, v33
	v_lshlrev_b32_e32 v0, 2, v0
	v_lshl_add_u64 v[20:21], v[58:59], 0, v[0:1]
	v_mul_u32_u24_e32 v0, 36, v33
	v_lshlrev_b32_e32 v0, 2, v0
	flat_load_dword v18, v[18:19] nt
	s_nop 0
	flat_load_dword v19, v[20:21] nt
	v_lshl_add_u64 v[20:21], v[58:59], 0, v[0:1]
	v_mul_u32_u24_e32 v0, 38, v33
	v_lshlrev_b32_e32 v0, 2, v0
	v_lshl_add_u64 v[22:23], v[58:59], 0, v[0:1]
	v_mul_u32_u24_e32 v0, 40, v33
	v_lshlrev_b32_e32 v0, 2, v0
	flat_load_dword v20, v[20:21] nt
	s_nop 0
	flat_load_dword v21, v[22:23] nt
	v_lshl_add_u64 v[22:23], v[58:59], 0, v[0:1]
	v_mul_u32_u24_e32 v0, 42, v33
	v_lshlrev_b32_e32 v0, 2, v0
	v_lshl_add_u64 v[24:25], v[58:59], 0, v[0:1]
	v_mul_u32_u24_e32 v0, 44, v33
	v_lshlrev_b32_e32 v0, 2, v0
	flat_load_dword v22, v[22:23] nt
	s_nop 0
	flat_load_dword v23, v[24:25] nt
	v_lshl_add_u64 v[24:25], v[58:59], 0, v[0:1]
	v_mul_u32_u24_e32 v0, 46, v33
	v_lshlrev_b32_e32 v0, 2, v0
	v_lshl_add_u64 v[26:27], v[58:59], 0, v[0:1]
	v_mul_u32_u24_e32 v0, 48, v33
	v_lshlrev_b32_e32 v0, 2, v0
	flat_load_dword v24, v[24:25] nt
	s_nop 0
	flat_load_dword v25, v[26:27] nt
	v_lshl_add_u64 v[26:27], v[58:59], 0, v[0:1]
	v_mul_u32_u24_e32 v0, 50, v33
	v_lshlrev_b32_e32 v0, 2, v0
	v_lshl_add_u64 v[28:29], v[58:59], 0, v[0:1]
	v_mul_u32_u24_e32 v0, 52, v33
	v_lshlrev_b32_e32 v0, 2, v0
	flat_load_dword v26, v[26:27] nt
	s_nop 0
	flat_load_dword v27, v[28:29] nt
	v_lshl_add_u64 v[28:29], v[58:59], 0, v[0:1]
	v_mul_u32_u24_e32 v0, 54, v33
	v_lshlrev_b32_e32 v0, 2, v0
	v_lshl_add_u64 v[30:31], v[58:59], 0, v[0:1]
	v_mul_u32_u24_e32 v0, 56, v33
	v_lshlrev_b32_e32 v0, 2, v0
	flat_load_dword v28, v[28:29] nt
	s_nop 0
	flat_load_dword v29, v[30:31] nt
	v_lshl_add_u64 v[30:31], v[58:59], 0, v[0:1]
	v_mul_u32_u24_e32 v0, 58, v33
	v_lshlrev_b32_e32 v0, 2, v0
	v_lshl_add_u64 v[60:61], v[58:59], 0, v[0:1]
	v_mul_u32_u24_e32 v0, 60, v33
	v_lshlrev_b32_e32 v0, 2, v0
	flat_load_dword v30, v[30:31] nt
	s_nop 0
	flat_load_dword v31, v[60:61] nt
	v_lshl_add_u64 v[60:61], v[58:59], 0, v[0:1]
	v_mul_u32_u24_e32 v0, 62, v33
	v_lshlrev_b32_e32 v0, 2, v0
	v_lshl_add_u64 v[58:59], v[58:59], 0, v[0:1]
	flat_load_dword v32, v[60:61] nt
	flat_load_dword v33, v[58:59] nt
.LBB0_725:
	s_or_b64 exec, exec, s[16:17]
	v_mov_b32_e32 v101, v64
	s_branch .LBB0_618

.LBB0_784:
	s_or_b64 exec, exec, s[6:7]
	v_readlane_b32 s0, v255, 10
	v_readlane_b32 s1, v255, 11
	s_waitcnt lgkmcnt(0)
	v_mov_b32_e32 v0, v254
	s_waitcnt vmcnt(0)
	v_mov_b64_e32 v[2:3], s[0:1]
	s_barrier
	flat_load_dwordx2 v[4:5], v[2:3] offset:200 sc0 sc1
	flat_load_dwordx2 v[6:7], v[2:3] offset:208 sc0 sc1
	flat_load_dwordx2 v[8:9], v[2:3] offset:216 sc0 sc1
	flat_load_dwordx2 v[2:3], v[2:3] offset:224 sc0 sc1
	s_waitcnt vmcnt(0)
	s_add_u32 s8, s26, 0xf200000
	v_readfirstlane_b32 s0, v0
	s_addc_u32 s9, s27, 0
	s_ashr_i32 s0, s0, 6
	v_readlane_b32 s1, v255, 6
	s_add_i32 s20, s0, s1
	s_cmp_lt_i32 s20, 0x10000
	s_waitcnt lgkmcnt(0)
	v_readfirstlane_b32 s11, v5
	v_readfirstlane_b32 s10, v4
	v_readfirstlane_b32 s13, v7
	v_readfirstlane_b32 s12, v6
	v_readfirstlane_b32 s15, v9
	v_readfirstlane_b32 s14, v8
	v_readfirstlane_b32 s17, v3
	v_readfirstlane_b32 s16, v2
	s_cbranch_scc0 .LBB0_787
	s_add_u32 s18, s26, 0xb200000
	s_addc_u32 s19, s27, 0
	v_lshlrev_b32_e32 v0, 2, v0
	s_lshl_b32 s1, s2, 11
	s_lshl_b32 s0, s0, 8
	v_and_b32_e32 v2, 0xfc, v0
	s_add_i32 s21, s1, s0
	s_lshl_b32 s23, s30, 11
	v_mov_b32_e32 v3, 0x3a27c5ac
	s_mov_b32 s24, 0xf800000
	v_mov_b32_e32 v4, 0x260
	v_mov_b32_e32 v1, 0
	s_movk_i32 s25, 0x1000

.LBB0_1012:
	v_readlane_b32 s0, v255, 10
	v_readlane_b32 s1, v255, 11
	v_lshl_add_u32 v24, v128, 2, 0
	s_nop 0
	v_mov_b64_e32 v[0:1], s[0:1]
	flat_load_dwordx2 v[2:3], v[0:1] offset:8 sc0 sc1
	flat_load_dwordx2 v[4:5], v[0:1] offset:32 sc0 sc1
	flat_load_dwordx2 v[6:7], v[0:1] offset:40 sc0 sc1
	s_waitcnt vmcnt(0)
	s_movk_i32 s0, 0x800
	v_cmp_gt_i32_e32 vcc, s0, v128
	s_waitcnt lgkmcnt(0)
	s_barrier
	v_readfirstlane_b32 s7, v3
	v_readfirstlane_b32 s6, v2
	v_readfirstlane_b32 s5, v5
	v_readfirstlane_b32 s4, v4
	v_readfirstlane_b32 s10, v7
	v_readfirstlane_b32 s11, v6
	s_and_saveexec_b64 s[0:1], vcc
	s_cbranch_execz .LBB0_1015
	v_ashrrev_i32_e32 v129, 31, v128
	v_add_u32_e32 v2, 0xfffffe00, v128
	v_lshl_add_u64 v[0:1], v[128:129], 2, s[6:7]
	s_mov_b64 s[6:7], 0
	s_mov_b32 s12, 0xbfb8aa3b
	s_mov_b32 s13, 0x42ce8ed0
	s_mov_b32 s15, 0xc2b17218
	v_mov_b32_e32 v3, 0x7f800000
	s_mov_b64 s[8:9], 0x800
	s_movk_i32 s16, 0x5ff
	v_mov_b32_e32 v4, v24

.LBB0_1292:
	s_or_b64 exec, exec, s[6:7]
	s_waitcnt lgkmcnt(0)
	v_mov_b32_e32 v0, v254
	v_mov_b64_e32 v[2:3], s[40:41]
	s_barrier
	flat_load_dwordx2 v[4:5], v[2:3] offset:248 sc0 sc1
	flat_load_dwordx2 v[6:7], v[2:3] offset:256 sc0 sc1
	s_waitcnt vmcnt(0)
	s_add_u32 s46, s26, 0xd200000
	s_addc_u32 s47, s27, 0
	s_add_u32 s54, s26, 0x9200000
	s_addc_u32 s55, s27, 0
	s_cmpk_lt_i32 s2, 0x1000
	s_waitcnt lgkmcnt(0)
	v_readfirstlane_b32 s9, v5
	v_readfirstlane_b32 s8, v4
	v_readfirstlane_b32 s11, v7
	v_readfirstlane_b32 s10, v6
	s_cbranch_scc0 .LBB0_1319
	v_ashrrev_i32_e32 v5, 4, v0
	v_lshlrev_b32_e32 v1, 2, v0
	v_ashrrev_i32_e32 v55, 3, v0
	v_lshlrev_b32_e32 v0, 3, v0
	s_add_u32 s12, s8, 0x6000
	v_and_b32_e32 v4, 56, v0
	s_movk_i32 s4, 0x41
	v_and_b32_e32 v54, 60, v1
	s_addc_u32 s13, s9, 0
	v_mad_u64_u32 v[0:1], s[0:1], v55, s4, v[4:5]
	s_add_u32 s14, s8, 0xc000
	v_lshl_add_u32 v56, v0, 2, 0
	v_mad_u32_u24 v0, v54, s4, v5
	s_addc_u32 s15, s9, 0
	v_mov_b32_e32 v7, 0
	v_or_b32_e32 v57, 0x800, v54
	v_or_b32_e32 v58, 0x1000, v54
	v_lshl_add_u32 v59, v0, 2, 0
	s_lshl_b32 s4, s2, 1
	s_lshl_b32 s5, s30, 1
	s_lshl_b32 s18, s2, 6
	s_lshl_b32 s19, s30, 6
	s_movk_i32 s20, 0x3000
	v_mov_b64_e32 v[8:9], s[48:49]
	s_movk_i32 s21, 0x1fff
	s_mov_b32 s23, 0xd200000
	s_mov_b32 s24, s2
	s_branch .LBB0_1295
